# MIX3: prev-state fragments prefetched + norm gains loaded once; MIX1 LayerNorm reductions via DPP/permlane swaps instead of ds_bpermute
# speedup vs baseline: 1.0524x; 1.0088x over previous
.LBB0_341:
	s_or_b64 exec, exec, s[26:27]
	s_mov_b64 s[16:17], s[46:47]
	s_waitcnt lgkmcnt(0)
	s_barrier
	s_add_u32 s26, s16, s64
	s_addc_u32 s27, s17, s65
	s_lshl_b64 s[16:17], s[24:25], 2
	s_add_u32 s16, s26, s16
	s_addc_u32 s17, s27, s17
	s_lshl_b32 s26, s29, 2
	s_add_i32 s26, s26, 0
	v_lshl_add_u32 v72, v124, 2, s26
	v_add_u32_e32 v82, 0x1000, v72
	ds_read2_b32 v[74:75], v82 offset1:16
	ds_read2_b32 v[76:77], v82 offset0:64 offset1:80
	ds_read2_b32 v[72:73], v82 offset0:128 offset1:144
	ds_read2_b32 v[78:79], v82 offset0:192 offset1:208
	v_lshlrev_b32_e32 v62, 2, v125
	s_waitcnt lgkmcnt(3)
	v_mov_b32_e32 v80, v74
	s_waitcnt lgkmcnt(2)
	v_mov_b32_e32 v86, v76
	s_waitcnt lgkmcnt(1)
	v_mov_b32_e32 v81, v72
	s_waitcnt lgkmcnt(0)
	v_mov_b32_e32 v87, v78
	v_pk_add_f32 v[80:81], v[80:81], v[86:87]
	v_mov_b32_e32 v63, v163
	v_add_f32_e32 v72, v80, v81
	v_fmamk_f32 v72, v72, 0x3b800000, v209
	v_cmp_gt_f32_e32 vcc, s5, v72
	v_mul_f32_e32 v74, 0x4f800000, v72
	v_lshl_add_u64 v[62:63], s[16:17], 0, v[62:63]
	global_load_dwordx4 v[166:169], v[62:63], off
	global_load_dwordx4 v[170:173], v[62:63], off offset:64
	global_load_dwordx4 v[174:177], v[62:63], off offset:128
	global_load_dwordx4 v[178:181], v[62:63], off offset:192
	v_cndmask_b32_e32 v72, v72, v74, vcc
	v_sqrt_f32_e32 v74, v72
	v_ashrrev_i32_e32 v85, 31, v84
	s_lshl_b64 s[24:25], s[24:25], 1
	v_ashrrev_i32_e32 v49, 31, v48
	v_add_u32_e32 v76, -1, v74
	v_fma_f32 v78, -v76, v74, v72
	v_cmp_ge_f32_e64 s[40:41], 0, v78
	v_add_u32_e32 v78, 1, v74
	v_lshlrev_b64 v[48:49], 11, v[48:49]
	v_cndmask_b32_e64 v76, v74, v76, s[40:41]
	v_fma_f32 v74, -v78, v74, v72
	v_cmp_lt_f32_e64 s[40:41], 0, v74
	v_ashrrev_i32_e32 v51, 31, v50
	v_ashrrev_i32_e32 v19, 31, v18
	v_cndmask_b32_e64 v74, v76, v78, s[40:41]
	v_mul_f32_e32 v76, 0x37800000, v74
	v_cndmask_b32_e32 v74, v74, v76, vcc
	v_cmp_class_f32_e32 vcc, v72, v210
	s_add_i32 s36, s36, s80
	s_add_i32 s51, s51, s66
	v_cndmask_b32_e32 v72, v74, v72, vcc
	v_div_scale_f32 v74, s[16:17], v72, v72, 1.0
	v_rcp_f32_e32 v76, v74
	s_cmpk_gt_i32 s36, 0xff
	v_fma_f32 v78, -v74, v76, 1.0
	v_fmac_f32_e32 v76, v78, v76
	v_div_scale_f32 v78, vcc, 1.0, v72, 1.0
	v_mul_f32_e32 v80, v78, v76
	v_fma_f32 v81, -v74, v80, v78
	v_fmac_f32_e32 v80, v81, v76
	v_fma_f32 v74, -v74, v80, v78
	v_div_fmas_f32 v74, v74, v76, v80
	v_lshlrev_b64 v[80:81], 11, v[84:85]
	v_div_fixup_f32 v72, v74, v72, 1.0
	v_pk_mul_f32 v[68:69], v[68:69], v[72:73] op_sel_hi:[1,0]
	v_pk_mul_f32 v[70:71], v[70:71], v[72:73] op_sel_hi:[1,0]
	v_pk_mul_f32 v[64:65], v[64:65], v[72:73] op_sel_hi:[1,0]
	v_pk_mul_f32 v[66:67], v[66:67], v[72:73] op_sel_hi:[1,0]
	v_pk_mul_f32 v[56:57], v[56:57], v[72:73] op_sel_hi:[1,0]
	v_pk_mul_f32 v[58:59], v[58:59], v[72:73] op_sel_hi:[1,0]
	v_pk_mul_f32 v[52:53], v[52:53], v[72:73] op_sel_hi:[1,0]
	v_pk_mul_f32 v[54:55], v[54:55], v[72:73] op_sel_hi:[1,0]
	v_mov_b32_e32 v72, v75
	v_mov_b32_e32 v78, v77
	s_waitcnt vmcnt(0) lgkmcnt(0)
	v_mov_b32_e32 v84, v166
	v_mov_b32_e32 v85, v167
	v_mov_b32_e32 v86, v168
	v_mov_b32_e32 v87, v169
	v_pk_mul_f32 v[68:69], v[84:85], v[68:69]
	v_pk_mul_f32 v[70:71], v[86:87], v[70:71]
	v_cvt_pk_bf16_f32 v68, v68, v69
	v_cvt_pk_bf16_f32 v69, v70, v71
	v_lshl_add_u64 v[70:71], s[18:19], 0, v[80:81]
	v_lshl_add_u64 v[70:71], v[70:71], 0, s[24:25]
	v_lshl_add_u64 v[80:81], v[70:71], 0, v[162:163]
	global_store_dwordx2 v[80:81], v[68:69], off offset:512
	s_waitcnt lgkmcnt(0)
	v_mov_b32_e32 v68, v170
	v_mov_b32_e32 v69, v171
	v_mov_b32_e32 v70, v172
	v_mov_b32_e32 v71, v173
	v_pk_mul_f32 v[64:65], v[68:69], v[64:65]
	v_pk_mul_f32 v[66:67], v[70:71], v[66:67]
	v_cvt_pk_bf16_f32 v64, v64, v65
	v_cvt_pk_bf16_f32 v65, v66, v67
	global_store_dwordx2 v[80:81], v[64:65], off offset:544
	s_waitcnt lgkmcnt(0)
	v_mov_b32_e32 v64, v174
	v_mov_b32_e32 v65, v175
	v_mov_b32_e32 v66, v176
	v_mov_b32_e32 v67, v177
	v_pk_mul_f32 v[56:57], v[64:65], v[56:57]
	v_pk_mul_f32 v[58:59], v[66:67], v[58:59]
	v_cvt_pk_bf16_f32 v56, v56, v57
	v_cvt_pk_bf16_f32 v57, v58, v59
	global_store_dwordx2 v[80:81], v[56:57], off offset:576
	s_waitcnt lgkmcnt(0)
	v_mov_b32_e32 v56, v178
	v_mov_b32_e32 v57, v179
	v_mov_b32_e32 v58, v180
	v_mov_b32_e32 v59, v181
	v_pk_mul_f32 v[52:53], v[52:53], v[56:57]
	v_pk_mul_f32 v[54:55], v[54:55], v[58:59]
	v_cvt_pk_bf16_f32 v52, v52, v53
	v_cvt_pk_bf16_f32 v53, v54, v55
	global_store_dwordx2 v[80:81], v[52:53], off offset:608
	v_pk_add_f32 v[52:53], v[72:73], v[78:79]
	s_nop 0
	v_add_f32_e32 v52, v52, v53
	v_fmamk_f32 v52, v52, 0x3b800000, v209
	v_cmp_gt_f32_e32 vcc, s5, v52
	v_mul_f32_e32 v53, 0x4f800000, v52
	s_nop 0
	v_cndmask_b32_e32 v52, v52, v53, vcc
	v_sqrt_f32_e32 v53, v52
	s_nop 0
	v_add_u32_e32 v54, -1, v53
	v_fma_f32 v55, -v54, v53, v52
	v_cmp_ge_f32_e64 s[40:41], 0, v55
	v_add_u32_e32 v55, 1, v53
	s_nop 0
	v_cndmask_b32_e64 v54, v53, v54, s[40:41]
	v_fma_f32 v53, -v55, v53, v52
	v_cmp_lt_f32_e64 s[40:41], 0, v53
	s_nop 1
	v_cndmask_b32_e64 v53, v54, v55, s[40:41]
	v_mul_f32_e32 v54, 0x37800000, v53
	v_cndmask_b32_e32 v53, v53, v54, vcc
	v_cmp_class_f32_e32 vcc, v52, v210
	s_nop 1
	v_cndmask_b32_e32 v52, v53, v52, vcc
	v_div_scale_f32 v53, s[16:17], v52, v52, 1.0
	v_rcp_f32_e32 v54, v53
	s_nop 0
	v_fma_f32 v55, -v53, v54, 1.0
	v_fmac_f32_e32 v54, v55, v54
	v_div_scale_f32 v55, vcc, 1.0, v52, 1.0
	v_mul_f32_e32 v56, v55, v54
	v_fma_f32 v57, -v53, v56, v55
	v_fmac_f32_e32 v56, v57, v54
	v_fma_f32 v53, -v53, v56, v55
	v_div_fmas_f32 v53, v53, v54, v56
	v_div_fixup_f32 v52, v53, v52, 1.0
	v_pk_mul_f32 v[44:45], v[44:45], v[52:53] op_sel_hi:[1,0]
	v_pk_mul_f32 v[46:47], v[46:47], v[52:53] op_sel_hi:[1,0]
	v_pk_mul_f32 v[40:41], v[40:41], v[52:53] op_sel_hi:[1,0]
	v_pk_mul_f32 v[42:43], v[42:43], v[52:53] op_sel_hi:[1,0]
	v_pk_mul_f32 v[36:37], v[36:37], v[52:53] op_sel_hi:[1,0]
	v_pk_mul_f32 v[38:39], v[38:39], v[52:53] op_sel_hi:[1,0]
	v_pk_mul_f32 v[28:29], v[28:29], v[52:53] op_sel_hi:[1,0]
	s_waitcnt lgkmcnt(0)
	v_mov_b32_e32 v54, v166
	v_mov_b32_e32 v55, v167
	v_mov_b32_e32 v56, v168
	v_mov_b32_e32 v57, v169
	v_pk_mul_f32 v[44:45], v[54:55], v[44:45]
	v_pk_mul_f32 v[46:47], v[56:57], v[46:47]
	v_cvt_pk_bf16_f32 v44, v44, v45
	v_cvt_pk_bf16_f32 v45, v46, v47
	v_lshl_add_u64 v[46:47], s[18:19], 0, v[48:49]
	v_lshl_add_u64 v[46:47], v[46:47], 0, s[24:25]
	v_lshl_add_u64 v[48:49], v[46:47], 0, v[162:163]
	global_store_dwordx2 v[48:49], v[44:45], off offset:512
	s_waitcnt lgkmcnt(0)
	v_mov_b32_e32 v44, v170
	v_mov_b32_e32 v45, v171
	v_mov_b32_e32 v46, v172
	v_mov_b32_e32 v47, v173
	v_pk_mul_f32 v[40:41], v[44:45], v[40:41]
	v_pk_mul_f32 v[42:43], v[46:47], v[42:43]
	v_cvt_pk_bf16_f32 v40, v40, v41
	v_cvt_pk_bf16_f32 v41, v42, v43
	global_store_dwordx2 v[48:49], v[40:41], off offset:544
	s_waitcnt lgkmcnt(0)
	v_mov_b32_e32 v40, v174
	v_mov_b32_e32 v41, v175
	v_mov_b32_e32 v42, v176
	v_mov_b32_e32 v43, v177
	v_pk_mul_f32 v[36:37], v[40:41], v[36:37]
	v_pk_mul_f32 v[38:39], v[42:43], v[38:39]
	v_cvt_pk_bf16_f32 v36, v36, v37
	v_cvt_pk_bf16_f32 v37, v38, v39
	global_store_dwordx2 v[48:49], v[36:37], off offset:576
	s_waitcnt lgkmcnt(0)
	v_mov_b32_e32 v36, v178
	v_mov_b32_e32 v37, v179
	v_mov_b32_e32 v38, v180
	v_mov_b32_e32 v39, v181
	v_pk_mul_f32 v[28:29], v[28:29], v[36:37]
	v_pk_mul_f32 v[36:37], v[60:61], v[52:53] op_sel_hi:[1,0]
	v_cvt_pk_bf16_f32 v28, v28, v29
	v_pk_mul_f32 v[36:37], v[36:37], v[38:39]
	s_nop 0
	v_cvt_pk_bf16_f32 v29, v36, v37
	global_store_dwordx2 v[48:49], v[28:29], off offset:608
	ds_read2_b32 v[36:37], v82 offset0:32 offset1:48
	ds_read2_b32 v[38:39], v82 offset0:96 offset1:112
	ds_read2_b32 v[28:29], v82 offset0:160 offset1:176
	ds_read2_b32 v[40:41], v82 offset0:224 offset1:240
	s_waitcnt lgkmcnt(3)
	v_mov_b32_e32 v42, v36
	s_waitcnt lgkmcnt(2)
	v_mov_b32_e32 v44, v38
	s_waitcnt lgkmcnt(1)
	v_mov_b32_e32 v43, v28
	s_waitcnt lgkmcnt(0)
	v_mov_b32_e32 v45, v40
	v_pk_add_f32 v[42:43], v[42:43], v[44:45]
	v_add_f32_e32 v28, v42, v43
	v_fmamk_f32 v28, v28, 0x3b800000, v209
	v_cmp_gt_f32_e32 vcc, s5, v28
	v_mul_f32_e32 v36, 0x4f800000, v28
	s_nop 0
	v_cndmask_b32_e32 v28, v28, v36, vcc
	v_sqrt_f32_e32 v36, v28
	s_nop 0
	v_add_u32_e32 v38, -1, v36
	v_fma_f32 v40, -v38, v36, v28
	v_cmp_ge_f32_e64 s[40:41], 0, v40
	v_add_u32_e32 v40, 1, v36
	s_nop 0
	v_cndmask_b32_e64 v38, v36, v38, s[40:41]
	v_fma_f32 v36, -v40, v36, v28
	v_cmp_lt_f32_e64 s[40:41], 0, v36
	s_nop 1
	v_cndmask_b32_e64 v36, v38, v40, s[40:41]
	v_mul_f32_e32 v38, 0x37800000, v36
	v_cndmask_b32_e32 v36, v36, v38, vcc
	v_cmp_class_f32_e32 vcc, v28, v210
	s_nop 1
	v_cndmask_b32_e32 v28, v36, v28, vcc
	v_div_scale_f32 v36, s[16:17], v28, v28, 1.0
	v_rcp_f32_e32 v38, v36
	s_nop 0
	v_fma_f32 v40, -v36, v38, 1.0
	v_fmac_f32_e32 v38, v40, v38
	v_div_scale_f32 v40, vcc, 1.0, v28, 1.0
	v_mul_f32_e32 v42, v40, v38
	v_fma_f32 v43, -v36, v42, v40
	v_fmac_f32_e32 v42, v43, v38
	v_fma_f32 v36, -v36, v42, v40
	v_div_fmas_f32 v36, v36, v38, v42
	v_div_fixup_f32 v28, v36, v28, 1.0
	v_pk_mul_f32 v[30:31], v[30:31], v[28:29] op_sel_hi:[1,0]
	v_pk_mul_f32 v[32:33], v[32:33], v[28:29] op_sel_hi:[1,0]
	v_lshlrev_b64 v[42:43], 11, v[50:51]
	v_pk_mul_f32 v[24:25], v[24:25], v[28:29] op_sel_hi:[1,0]
	v_pk_mul_f32 v[26:27], v[26:27], v[28:29] op_sel_hi:[1,0]
	v_pk_mul_f32 v[20:21], v[20:21], v[28:29] op_sel_hi:[1,0]
	v_pk_mul_f32 v[22:23], v[22:23], v[28:29] op_sel_hi:[1,0]
	v_pk_mul_f32 v[16:17], v[16:17], v[28:29] op_sel_hi:[1,0]
	v_mov_b32_e32 v40, v39
	s_waitcnt lgkmcnt(0)
	v_mov_b32_e32 v44, v166
	v_mov_b32_e32 v45, v167
	v_mov_b32_e32 v46, v168
	v_mov_b32_e32 v47, v169
	v_pk_mul_f32 v[30:31], v[44:45], v[30:31]
	v_pk_mul_f32 v[32:33], v[46:47], v[32:33]
	v_cvt_pk_bf16_f32 v30, v30, v31
	v_cvt_pk_bf16_f32 v31, v32, v33
	v_lshl_add_u64 v[32:33], s[18:19], 0, v[42:43]
	v_lshl_add_u64 v[32:33], v[32:33], 0, s[24:25]
	v_lshl_add_u64 v[42:43], v[32:33], 0, v[162:163]
	global_store_dwordx2 v[42:43], v[30:31], off offset:512
	s_waitcnt lgkmcnt(0)
	v_mov_b32_e32 v30, v170
	v_mov_b32_e32 v31, v171
	v_mov_b32_e32 v32, v172
	v_mov_b32_e32 v33, v173
	v_pk_mul_f32 v[24:25], v[30:31], v[24:25]
	v_pk_mul_f32 v[26:27], v[32:33], v[26:27]
	v_cvt_pk_bf16_f32 v24, v24, v25
	v_cvt_pk_bf16_f32 v25, v26, v27
	global_store_dwordx2 v[42:43], v[24:25], off offset:544
	s_waitcnt lgkmcnt(0)
	v_mov_b32_e32 v24, v174
	v_mov_b32_e32 v25, v175
	v_mov_b32_e32 v26, v176
	v_mov_b32_e32 v27, v177
	v_pk_mul_f32 v[20:21], v[24:25], v[20:21]
	v_pk_mul_f32 v[22:23], v[26:27], v[22:23]
	v_cvt_pk_bf16_f32 v20, v20, v21
	v_cvt_pk_bf16_f32 v21, v22, v23
	global_store_dwordx2 v[42:43], v[20:21], off offset:576
	s_waitcnt lgkmcnt(0)
	v_mov_b32_e32 v20, v178
	v_mov_b32_e32 v21, v179
	v_mov_b32_e32 v22, v180
	v_mov_b32_e32 v23, v181
	v_pk_mul_f32 v[16:17], v[16:17], v[20:21]
	v_pk_mul_f32 v[20:21], v[34:35], v[28:29] op_sel_hi:[1,0]
	v_cvt_pk_bf16_f32 v16, v16, v17
	v_pk_mul_f32 v[20:21], v[20:21], v[22:23]
	v_mov_b32_e32 v28, v37
	v_cvt_pk_bf16_f32 v17, v20, v21
	global_store_dwordx2 v[42:43], v[16:17], off offset:608
	v_pk_add_f32 v[16:17], v[28:29], v[40:41]
	s_nop 0
	v_add_f32_e32 v16, v16, v17
	v_fmamk_f32 v16, v16, 0x3b800000, v209
	v_cmp_gt_f32_e32 vcc, s5, v16
	v_mul_f32_e32 v17, 0x4f800000, v16
	s_nop 0
	v_cndmask_b32_e32 v16, v16, v17, vcc
	v_sqrt_f32_e32 v17, v16
	s_nop 0
	v_add_u32_e32 v20, -1, v17
	v_fma_f32 v21, -v20, v17, v16
	v_cmp_ge_f32_e64 s[40:41], 0, v21
	v_add_u32_e32 v21, 1, v17
	s_nop 0
	v_cndmask_b32_e64 v20, v17, v20, s[40:41]
	v_fma_f32 v17, -v21, v17, v16
	v_cmp_lt_f32_e64 s[40:41], 0, v17
	s_nop 1
	v_cndmask_b32_e64 v17, v20, v21, s[40:41]
	v_mul_f32_e32 v20, 0x37800000, v17
	v_cndmask_b32_e32 v17, v17, v20, vcc
	v_cmp_class_f32_e32 vcc, v16, v210
	s_nop 1
	v_cndmask_b32_e32 v16, v17, v16, vcc
	v_div_scale_f32 v17, s[16:17], v16, v16, 1.0
	v_rcp_f32_e32 v20, v17
	s_nop 0
	v_fma_f32 v21, -v17, v20, 1.0
	v_fmac_f32_e32 v20, v21, v20
	v_div_scale_f32 v21, vcc, 1.0, v16, 1.0
	v_mul_f32_e32 v22, v21, v20
	v_fma_f32 v23, -v17, v22, v21
	v_fmac_f32_e32 v22, v23, v20
	v_fma_f32 v17, -v17, v22, v21
	v_div_fmas_f32 v17, v17, v20, v22
	v_lshlrev_b64 v[22:23], 11, v[18:19]
	v_div_fixup_f32 v16, v17, v16, 1.0
	v_pk_mul_f32 v[12:13], v[12:13], v[16:17] op_sel_hi:[1,0]
	v_pk_mul_f32 v[14:15], v[14:15], v[16:17] op_sel_hi:[1,0]
	v_pk_mul_f32 v[8:9], v[8:9], v[16:17] op_sel_hi:[1,0]
	v_pk_mul_f32 v[10:11], v[10:11], v[16:17] op_sel_hi:[1,0]
	v_pk_mul_f32 v[4:5], v[4:5], v[16:17] op_sel_hi:[1,0]
	v_pk_mul_f32 v[6:7], v[6:7], v[16:17] op_sel_hi:[1,0]
	v_pk_mul_f32 v[0:1], v[0:1], v[16:17] op_sel_hi:[1,0]
	v_pk_mul_f32 v[2:3], v[2:3], v[16:17] op_sel_hi:[1,0]
	s_waitcnt lgkmcnt(0)
	v_mov_b32_e32 v18, v166
	v_mov_b32_e32 v19, v167
	v_mov_b32_e32 v20, v168
	v_mov_b32_e32 v21, v169
	v_pk_mul_f32 v[12:13], v[18:19], v[12:13]
	v_pk_mul_f32 v[14:15], v[20:21], v[14:15]
	v_cvt_pk_bf16_f32 v12, v12, v13
	v_cvt_pk_bf16_f32 v13, v14, v15
	v_lshl_add_u64 v[14:15], s[18:19], 0, v[22:23]
	v_lshl_add_u64 v[14:15], v[14:15], 0, s[24:25]
	v_lshl_add_u64 v[18:19], v[14:15], 0, v[162:163]
	global_store_dwordx2 v[18:19], v[12:13], off offset:512
	s_waitcnt lgkmcnt(0)
	v_mov_b32_e32 v12, v170
	v_mov_b32_e32 v13, v171
	v_mov_b32_e32 v14, v172
	v_mov_b32_e32 v15, v173
	v_pk_mul_f32 v[8:9], v[12:13], v[8:9]
	v_pk_mul_f32 v[10:11], v[14:15], v[10:11]
	v_cvt_pk_bf16_f32 v8, v8, v9
	v_cvt_pk_bf16_f32 v9, v10, v11
	global_store_dwordx2 v[18:19], v[8:9], off offset:544
	s_waitcnt lgkmcnt(0)
	v_mov_b32_e32 v8, v174
	v_mov_b32_e32 v9, v175
	v_mov_b32_e32 v10, v176
	v_mov_b32_e32 v11, v177
	v_pk_mul_f32 v[4:5], v[8:9], v[4:5]
	v_pk_mul_f32 v[6:7], v[10:11], v[6:7]
	v_cvt_pk_bf16_f32 v4, v4, v5
	v_cvt_pk_bf16_f32 v5, v6, v7
	global_store_dwordx2 v[18:19], v[4:5], off offset:576
	s_waitcnt lgkmcnt(0)
	v_mov_b32_e32 v4, v178
	v_mov_b32_e32 v5, v179
	v_mov_b32_e32 v6, v180
	v_mov_b32_e32 v7, v181
	v_pk_mul_f32 v[0:1], v[0:1], v[4:5]
	v_pk_mul_f32 v[2:3], v[2:3], v[6:7]
	v_cvt_pk_bf16_f32 v0, v0, v1
	v_cvt_pk_bf16_f32 v1, v2, v3
	global_store_dwordx2 v[18:19], v[0:1], off offset:608
	s_barrier
	s_cbranch_scc1 .LBB0_387
.LBB0_342:
	v_mov_b32_e32 v24, v164
	s_and_b32 s17, s36, 0x7f
	v_readfirstlane_b32 s16, v24
	s_ashr_i32 s28, s16, 6
	s_lshl_b32 s67, s36, 6
	s_mov_b64 s[24:25], s[52:53]
	s_add_u32 s30, s24, s60
	s_addc_u32 s31, s25, s61
	s_mov_b64 s[24:25], s[54:55]
	v_and_b32_e32 v25, 63, v24
	s_add_u32 s24, s24, s62
	v_or_b32_e32 v0, s67, v25
	s_addc_u32 s25, s25, s63
	s_add_i32 s26, s28, s15
	v_ashrrev_i32_e32 v1, 31, v0
	s_ashr_i32 s27, s26, 31
	v_lshlrev_b64 v[0:1], 5, v[0:1]
	s_ashr_i32 s29, s28, 31
	s_lshl_b64 s[26:27], s[26:27], 2
	v_lshl_add_u64 v[0:1], s[22:23], 0, v[0:1]
	s_add_u32 s34, s56, s26
	v_lshl_add_u64 v[0:1], s[28:29], 2, v[0:1]
	s_addc_u32 s35, s57, s27
	global_load_dword v0, v[0:1], off
	s_nop 0
	global_load_dword v1, v163, s[34:35]
	s_add_u32 s34, s58, s26
	s_addc_u32 s35, s59, s27
	global_load_dword v2, v163, s[34:35]
	s_mov_b32 s0, 0xb2a5705f
	v_lshlrev_b32_e32 v128, 2, v25
	v_cmp_gt_u32_e64 s[40:41], 16, v25
	v_xor_b32_e32 v119, 0x80, v128
	s_cmp_eq_u32 s17, 0
	s_waitcnt vmcnt(0)
	v_add_f32_e32 v0, v0, v1
	v_mul_f32_e64 v1, |v0|, s48
	v_fma_f32 v4, |v0|, s48, -v1
	v_rndne_f32_e32 v5, v1
	v_fma_f32 v4, |v0|, s0, v4
	v_sub_f32_e32 v1, v1, v5
	s_waitcnt vmcnt(0)
	v_mov_b32_e32 v206, s36
	v_lshl_add_u32 v206, v206, 3, s28
	v_lshlrev_b32_e32 v206, 14, v206
	v_and_b32_e32 v207, 48, v25
	v_add_u32_e32 v206, v206, v207
	v_and_b32_e32 v207, 15, v24
	v_lshl_add_u32 v206, v207, 8, v206
	v_mov_b32_e32 v207, 0
	s_mov_b32 s100, s37
	s_mov_b32 s101, s38
	v_lshl_add_u64 v[206:207], s[100:101], 0, v[206:207]
	s_mov_b32 s100, 0x1000
	s_mov_b32 s101, 0
	global_load_dwordx4 v[166:169], v[206:207], off
	global_load_dwordx4 v[182:185], v[206:207], off offset:64
	global_load_dwordx4 v[198:201], v[206:207], off offset:128
	global_load_dwordx4 v[238:241], v[206:207], off offset:192
	v_lshl_add_u64 v[206:207], v[206:207], 0, s[100:101]
	global_load_dwordx4 v[170:173], v[206:207], off
	global_load_dwordx4 v[186:189], v[206:207], off offset:64
	global_load_dwordx4 v[202:205], v[206:207], off offset:128
	global_load_dwordx4 v[242:245], v[206:207], off offset:192
	v_lshl_add_u64 v[206:207], v[206:207], 0, s[100:101]
	global_load_dwordx4 v[174:177], v[206:207], off
	global_load_dwordx4 v[190:193], v[206:207], off offset:64
	global_load_dwordx4 v[230:233], v[206:207], off offset:128
	global_load_dwordx4 v[246:249], v[206:207], off offset:192
	v_lshl_add_u64 v[206:207], v[206:207], 0, s[100:101]
	global_load_dwordx4 v[178:181], v[206:207], off
	global_load_dwordx4 v[194:197], v[206:207], off offset:64
	global_load_dwordx4 v[234:237], v[206:207], off offset:128
	global_load_dwordx4 v[250:253], v[206:207], off offset:192
	v_mul_f32_e32 v6, 0x3fb8aa3b, v2
	v_add_f32_e32 v1, v1, v4
	v_cvt_i32_f32_e32 v5, v5
	v_fma_f32 v7, v2, s4, -v6
	v_rndne_f32_e32 v8, v6
	v_exp_f32_e32 v1, v1
	v_fmac_f32_e32 v7, 0x32a5705f, v2
	v_sub_f32_e32 v4, v6, v8
	v_add_f32_e32 v4, v4, v7
	v_cvt_i32_f32_e32 v6, v8
	v_exp_f32_e32 v4, v4
	s_mov_b32 s0, 0x42ce8ed0
	v_ldexp_f32 v1, v1, v5
	v_cmp_ngt_f32_e64 vcc, |v0|, s0
	s_mov_b32 s0, 0xc2b17218
	v_ldexp_f32 v4, v4, v6
	v_cndmask_b32_e32 v1, 0, v1, vcc
	v_cmp_nlt_f32_e64 vcc, |v0|, s0
	v_max_f32_e32 v3, 0, v0
	s_mov_b32 s0, 0x3f2aaaab
	v_cndmask_b32_e32 v5, v220, v1, vcc
	v_add_f32_e32 v6, 1.0, v5
	v_cmp_ngt_f32_e32 vcc, s82, v2
	v_add_f32_e32 v7, -1.0, v6
	v_frexp_mant_f32_e32 v8, v6
	v_cvt_f64_f32_e32 v[0:1], v6
	v_cndmask_b32_e32 v4, 0, v4, vcc
	v_sub_f32_e32 v9, v7, v6
	v_frexp_exp_i32_f64_e32 v0, v[0:1]
	v_cmp_gt_f32_e32 vcc, s0, v8
	v_sub_f32_e32 v7, v5, v7
	v_add_f32_e32 v1, 1.0, v9
	v_subbrev_co_u32_e32 v0, vcc, 0, v0, vcc
	v_add_f32_e32 v1, v7, v1
	v_sub_u32_e32 v7, 0, v0
	v_cvt_f32_i32_e32 v0, v0
	v_ldexp_f32 v6, v6, v7
	v_ldexp_f32 v1, v1, v7
	v_add_f32_e32 v7, -1.0, v6
	v_add_f32_e32 v8, 1.0, v6
	v_add_f32_e32 v9, 1.0, v7
	v_add_f32_e32 v10, -1.0, v8
	v_sub_f32_e32 v9, v6, v9
	v_sub_f32_e32 v6, v6, v10
	v_mul_f32_e32 v10, 0x3f317218, v0
	v_add_f32_e32 v9, v1, v9
	v_add_f32_e32 v1, v1, v6
	s_mov_b32 s0, 0x3f317218
	v_fma_f32 v6, v0, s0, -v10
	v_add_f32_e32 v11, v7, v9
	v_add_f32_e32 v12, v8, v1
	v_fmac_f32_e32 v6, 0xb102e308, v0
	v_sub_f32_e32 v0, v7, v11
	v_sub_f32_e32 v7, v8, v12
	v_rcp_f32_e32 v8, v12
	v_add_f32_e32 v13, v10, v6
	v_add_f32_e32 v1, v1, v7
	v_sub_f32_e32 v7, v13, v10
	v_sub_f32_e32 v6, v6, v7
	v_mul_f32_e32 v7, v11, v8
	v_add_f32_e32 v0, v9, v0
	v_mul_f32_e32 v9, v12, v7
	v_fma_f32 v10, v7, v12, -v9
	v_fmac_f32_e32 v10, v7, v1
	v_add_f32_e32 v14, v9, v10
	v_sub_f32_e32 v15, v11, v14
	v_sub_f32_e32 v9, v14, v9
	v_sub_f32_e32 v11, v11, v15
	v_sub_f32_e32 v9, v9, v10
	v_sub_f32_e32 v10, v11, v14
	v_add_f32_e32 v0, v0, v10
	v_add_f32_e32 v0, v9, v0
	v_add_f32_e32 v9, v15, v0
	v_mul_f32_e32 v10, v8, v9
	v_sub_f32_e32 v11, v15, v9
	v_mul_f32_e32 v14, v12, v10
	v_add_f32_e32 v0, v0, v11
	v_add_f32_e32 v11, v7, v10
	v_fma_f32 v12, v10, v12, -v14
	v_sub_f32_e32 v7, v11, v7
	v_fmac_f32_e32 v12, v10, v1
	v_sub_f32_e32 v1, v10, v7
	v_add_f32_e32 v7, v14, v12
	v_sub_f32_e32 v10, v7, v14
	v_sub_f32_e32 v14, v9, v7
	v_sub_f32_e32 v9, v9, v14
	v_sub_f32_e32 v7, v9, v7
	v_sub_f32_e32 v10, v10, v12
	v_add_f32_e32 v0, v0, v7
	v_add_f32_e32 v0, v10, v0
	v_add_f32_e32 v0, v14, v0
	v_mul_f32_e32 v0, v8, v0
	v_add_f32_e32 v0, v1, v0
	v_add_f32_e32 v1, v11, v0
	v_mul_f32_e32 v7, v1, v1
	v_fmamk_f32 v10, v7, 0x3e9b6dac, v208
	v_sub_f32_e32 v8, v1, v11
	v_ldexp_f32 v9, v1, 1
	v_mul_f32_e32 v1, v1, v7
	v_fmaak_f32 v7, v7, v10, 0x3f2aaada
	v_mul_f32_e32 v1, v1, v7
	v_add_f32_e32 v7, v9, v1
	v_sub_f32_e32 v0, v0, v8
	v_sub_f32_e32 v8, v7, v9
	v_ldexp_f32 v0, v0, 1
	v_sub_f32_e32 v1, v1, v8
	v_add_f32_e32 v0, v0, v1
	v_add_f32_e32 v1, v7, v0
	v_sub_f32_e32 v7, v1, v7
	v_add_f32_e32 v8, v13, v1
	v_sub_f32_e32 v0, v0, v7
	v_sub_f32_e32 v7, v8, v13
	v_sub_f32_e32 v9, v8, v7
	v_sub_f32_e32 v1, v1, v7
	v_add_f32_e32 v7, v6, v0
	v_sub_f32_e32 v9, v13, v9
	v_sub_f32_e32 v10, v7, v6
	v_add_f32_e32 v1, v1, v9
	v_sub_f32_e32 v9, v7, v10
	v_sub_f32_e32 v0, v0, v10
	v_sub_f32_e32 v6, v6, v9
	v_add_f32_e32 v1, v7, v1
	v_add_f32_e32 v0, v0, v6
	v_add_f32_e32 v6, v8, v1
	v_sub_f32_e32 v7, v6, v8
	v_sub_f32_e32 v1, v1, v7
	v_add_f32_e32 v0, v0, v1
	s_mov_b32 s0, 0x7f800000
	v_add_f32_e32 v0, v6, v0
	v_cmp_neq_f32_e32 vcc, s0, v5
	s_mov_b32 s0, 0x33800000
	v_lshlrev_b32_e32 v10, 1, v24
	v_cndmask_b32_e32 v0, v220, v0, vcc
	v_cmp_lt_f32_e64 vcc, |v5|, s0
	s_movk_i32 s0, 0xffc0
	v_ashrrev_i32_e32 v11, 31, v10
	v_cndmask_b32_e32 v0, v0, v5, vcc
	v_cmp_nlt_f32_e32 vcc, s49, v2
	v_add_f32_e32 v0, v3, v0
	v_add_u32_e32 v3, 0xfc, v128
	v_cndmask_b32_e32 v1, v220, v4, vcc
	v_mul_f32_e64 v2, v0, -v1
	v_and_b32_e32 v3, 0xfc, v3
	ds_bpermute_b32 v3, v3, v2
	v_cmp_eq_u32_e32 vcc, 0, v25
	v_lshlrev_b64 v[8:9], 2, v[10:11]
	s_waitcnt lgkmcnt(0)
	v_fma_f32 v1, v0, -v1, v3
	v_cndmask_b32_e32 v1, v1, v2, vcc
	v_add_u32_e32 v2, 0xf8, v128
	v_and_b32_e32 v2, 0xfc, v2
	ds_bpermute_b32 v2, v2, v1
	v_cmp_gt_u32_e32 vcc, 2, v25
	v_add_u32_e32 v3, 0xc0, v128
	s_waitcnt lgkmcnt(0)
	v_add_f32_e32 v2, v1, v2
	v_cndmask_b32_e32 v1, v2, v1, vcc
	v_add_u32_e32 v2, 0xf0, v128
	v_and_b32_e32 v2, 0xfc, v2
	ds_bpermute_b32 v2, v2, v1
	v_cmp_gt_u32_e32 vcc, 4, v25
	s_waitcnt lgkmcnt(0)
	v_add_f32_e32 v2, v1, v2
	v_cndmask_b32_e32 v1, v2, v1, vcc
	v_add_u32_e32 v2, 0xe0, v128
	v_and_b32_e32 v2, 0xfc, v2
	ds_bpermute_b32 v2, v2, v1
	v_cmp_gt_u32_e32 vcc, 8, v25
	s_waitcnt lgkmcnt(0)
	v_add_f32_e32 v2, v1, v2
	v_cndmask_b32_e32 v1, v2, v1, vcc
	v_and_b32_e32 v2, 0xfc, v3
	ds_bpermute_b32 v2, v2, v1
	v_mov_b32_e32 v3, s16
	v_bfi_b32 v3, s0, v3, v24
	v_cmp_gt_u32_e32 vcc, 32, v25
	v_lshl_add_u32 v3, v3, 2, 0
	s_waitcnt lgkmcnt(0)
	v_add_f32_e32 v2, v1, v2
	v_cndmask_b32_e64 v1, v2, v1, s[40:41]
	ds_bpermute_b32 v2, v119, v1
	s_waitcnt lgkmcnt(0)
	v_add_f32_e32 v2, v1, v2
	v_cndmask_b32_e32 v1, v2, v1, vcc
	ds_write2st64_b32 v3, v0, v1 offset1:8
	v_lshl_add_u64 v[0:1], s[30:31], 0, v[8:9]
	v_add_co_u32_e32 v2, vcc, 0x1000, v0
	v_lshl_add_u64 v[8:9], s[24:25], 0, v[8:9]
	s_nop 0
	v_addc_co_u32_e32 v3, vcc, 0, v1, vcc
	v_add_co_u32_e32 v4, vcc, 0x2000, v0
	s_nop 1
	v_addc_co_u32_e32 v5, vcc, 0, v1, vcc
	v_add_co_u32_e32 v6, vcc, 0x3000, v0
	s_nop 1
	v_addc_co_u32_e32 v7, vcc, 0, v1, vcc
	flat_load_dwordx2 v[0:1], v[0:1]
	s_nop 0
	flat_load_dwordx2 v[2:3], v[2:3]
	s_nop 0
	flat_load_dwordx2 v[4:5], v[4:5]
	s_nop 0
	flat_load_dwordx2 v[6:7], v[6:7]
	s_nop 0
	flat_load_dwordx2 v[8:9], v[8:9]
	s_cbranch_scc1 .LBB0_344
	s_mul_i32 s24, s67, 0x1600
	s_mul_hi_i32 s17, s67, 0x1600
	s_add_u32 s24, s20, s24
	s_addc_u32 s25, s21, s17
	v_lshl_add_u64 v[12:13], v[10:11], 1, s[24:25]
	v_add_co_u32_e32 v14, vcc, 0xffffd000, v12
	s_nop 1
	v_addc_co_u32_e32 v15, vcc, -1, v13, vcc
	global_load_dword v16, v[14:15], off offset:-2048
	v_add_co_u32_e32 v14, vcc, 0xffffe000, v12
	s_nop 1
	v_addc_co_u32_e32 v15, vcc, -1, v13, vcc
	global_load_dword v14, v[14:15], off offset:-512
	s_nop 0
	global_load_dword v15, v[12:13], off offset:-3072
	s_waitcnt vmcnt(0)
	v_lshlrev_b32_e32 v12, 16, v16
	v_and_b32_e32 v13, 0xffff0000, v16
	v_lshlrev_b32_e32 v16, 16, v14
	v_and_b32_e32 v17, 0xffff0000, v14
	v_lshlrev_b32_e32 v14, 16, v15
	v_and_b32_e32 v15, 0xffff0000, v15
	s_branch .LBB0_345

.LBB0_379:
	s_lshl_b32 s17, s28, 4
	s_and_b32 s29, s16, 0xffffff00
	v_and_b32_e32 v124, 15, v24
	s_and_b32 s17, s17, 48
	v_and_b32_e32 v46, 48, v25
	s_add_i32 s25, s29, 0
	v_or_b32_e32 v0, s17, v124
	v_add_u32_e32 v34, s25, v46
	v_mad_u32_u24 v42, v0, s77, v34
	s_waitcnt lgkmcnt(0)
	s_barrier
	ds_read_b128 v[0:3], v42 offset:8192
	v_mad_u32_u24 v48, v124, s77, v223
	v_mad_u32_u24 v43, v124, s77, v34
	v_add_u32_e32 v44, v34, v48
	ds_read_b128 v[4:7], v43 offset:41984
	ds_read_b128 v[8:11], v42 offset:8256
	ds_read_b128 v[12:15], v43 offset:42048
	ds_read_b128 v[16:19], v44 offset:41984
	ds_read_b128 v[20:23], v44 offset:42048
	s_waitcnt lgkmcnt(4)
	v_mfma_f32_16x16x32_bf16 v[4:7], v[0:3], v[4:7], 0
	v_mad_u32_u24 v49, v124, s77, v224
	v_mad_u32_u24 v50, v124, s77, v225
	v_add_u32_e32 v45, v34, v49
	s_waitcnt lgkmcnt(1)
	v_mfma_f32_16x16x32_bf16 v[16:19], v[0:3], v[16:19], 0
	v_add_u32_e32 v47, v34, v50
	ds_read_b128 v[26:29], v45 offset:41984
	ds_read_b128 v[30:33], v45 offset:42048
	ds_read_b128 v[34:37], v47 offset:41984
	ds_read_b128 v[38:41], v47 offset:42048
	v_mfma_f32_16x16x32_bf16 v[4:7], v[8:11], v[12:15], v[4:7]
	s_ashr_i32 s16, s16, 8
	s_lshl_b32 s16, s16, 6
	v_lshlrev_b32_e32 v66, 8, v124
	s_waitcnt lgkmcnt(4)
	v_mfma_f32_16x16x32_bf16 v[12:15], v[8:11], v[20:23], v[16:19]
	ds_read_b128 v[20:23], v42 offset:8320
	v_mov_b32_e32 v67, v163
	v_or_b32_e32 v130, 16, v124
	s_waitcnt lgkmcnt(4)
	v_mfma_f32_16x16x32_bf16 v[26:29], v[0:3], v[26:29], 0
	v_or_b32_e32 v129, 32, v124
	v_or_b32_e32 v127, 48, v124
	s_waitcnt lgkmcnt(2)
	v_mfma_f32_16x16x32_bf16 v[0:3], v[0:3], v[34:37], 0
	v_mfma_f32_16x16x32_bf16 v[16:19], v[8:11], v[30:33], v[26:29]
	s_waitcnt lgkmcnt(1)
	v_mfma_f32_16x16x32_bf16 v[0:3], v[8:11], v[38:41], v[0:3]
	ds_read_b128 v[8:11], v43 offset:42112
	ds_read_b128 v[26:29], v42 offset:8384
	ds_read_b128 v[30:33], v43 offset:42176
	s_waitcnt lgkmcnt(2)
	v_mfma_f32_16x16x32_bf16 v[4:7], v[20:23], v[8:11], v[4:7]
	ds_read_b128 v[8:11], v44 offset:42112
	ds_read_b128 v[34:37], v44 offset:42176
	s_waitcnt lgkmcnt(1)
	v_mfma_f32_16x16x32_bf16 v[12:15], v[20:23], v[8:11], v[12:15]
	ds_read_b128 v[8:11], v45 offset:42112
	ds_read_b128 v[38:41], v45 offset:42176
	s_waitcnt lgkmcnt(1)
	v_mfma_f32_16x16x32_bf16 v[16:19], v[20:23], v[8:11], v[16:19]
	ds_read_b128 v[8:11], v47 offset:42112
	ds_read_b128 v[42:45], v47 offset:42176
	v_mov_b32_e32 v47, v163
	s_waitcnt lgkmcnt(0)
	v_mfma_f32_16x16x32_bf16 v[0:3], v[20:23], v[8:11], v[0:3]
	v_lshrrev_b32_e32 v10, 4, v25
	v_lshlrev_b32_e32 v125, 2, v10
	v_or_b32_e32 v8, s16, v125
	v_or_b32_e32 v8, s17, v8
	s_lshl_b32 s17, s36, 3
	s_add_i32 s30, s28, s17
	v_mfma_f32_16x16x32_bf16 v[4:7], v[26:29], v[30:33], v[4:7]
	s_ashr_i32 s31, s30, 31
	v_mul_lo_u32 v8, v8, s79
	s_lshl_b64 s[30:31], s[30:31], 14
	v_mfma_f32_16x16x32_bf16 v[20:23], v[26:29], v[34:37], v[12:15]
	s_add_u32 s30, s37, s30
	s_addc_u32 s31, s38, s31
	s_barrier
	v_lshlrev_b32_e32 v12, 2, v124
	v_add3_u32 v8, 0, v12, v8
	v_add_u32_e32 v8, 0xa400, v8
	v_mfma_f32_16x16x32_bf16 v[14:17], v[26:29], v[38:41], v[16:19]
	v_and_b32_e32 v11, 48, v24
	v_add_u32_e32 v13, s25, v11
	v_mad_u32_u24 v104, v124, s77, v13
	v_mfma_f32_16x16x32_bf16 v[0:3], v[26:29], v[42:45], v[0:3]
	ds_write2_b32 v8, v4, v20 offset1:16
	ds_write2_b32 v8, v5, v21 offset0:66 offset1:82
	ds_write2_b32 v8, v6, v22 offset0:132 offset1:148
	ds_write2_b32 v8, v7, v23 offset0:198 offset1:214
	s_nop 3
	ds_write2_b32 v8, v14, v0 offset0:32 offset1:48
	ds_write2_b32 v8, v15, v1 offset0:98 offset1:114
	ds_write2_b32 v8, v16, v2 offset0:164 offset1:180
	ds_write2_b32 v8, v17, v3 offset0:230 offset1:246
	v_lshl_add_u64 v[8:9], s[30:31], 0, v[46:47]
	v_lshl_add_u64 v[6:7], v[8:9], 0, v[66:67]
	s_waitcnt lgkmcnt(0)
	s_barrier
	v_add_u32_e32 v105, v13, v48
	v_add_u32_e32 v106, v13, v49
	v_add_u32_e32 v13, v13, v50
	ds_read_b128 v[18:21], v104 offset:8192
	ds_read_b128 v[38:41], v13 offset:8192
	ds_read_b128 v[22:25], v105 offset:8192
	ds_read_b128 v[34:37], v106 offset:8192
	v_or_b32_e32 v4, 0x1000, v66
	v_mov_b32_e32 v5, v163
	v_lshl_add_u64 v[14:15], v[8:9], 0, v[4:5]
	v_lshlrev_b32_e32 v162, 3, v10
	s_waitcnt vmcnt(0) lgkmcnt(3)
	v_mov_b32_e32 v0, v166
	v_mov_b32_e32 v1, v167
	v_mov_b32_e32 v2, v168
	v_mov_b32_e32 v3, v169
	s_nop 1
	v_mfma_f32_16x16x32_bf16 v[26:29], v[0:3], v[18:21], 0
	s_waitcnt lgkmcnt(1)
	v_mfma_f32_16x16x32_bf16 v[30:33], v[0:3], v[22:25], 0
	s_waitcnt lgkmcnt(0)
	v_mfma_f32_16x16x32_bf16 v[42:45], v[0:3], v[34:37], 0
	v_mfma_f32_16x16x32_bf16 v[46:49], v[0:3], v[38:41], 0
	v_mov_b32_e32 v3, v163
	v_or_b32_e32 v2, 0x2000, v66
	v_lshl_add_u64 v[0:1], v[8:9], 0, v[2:3]
	v_or_b32_e32 v0, 0x3000, v66
	v_mov_b32_e32 v1, v163
	v_lshl_add_u64 v[66:67], v[8:9], 0, v[0:1]
	v_mov_b32_e32 v14, v170
	v_mov_b32_e32 v15, v171
	v_mov_b32_e32 v16, v172
	v_mov_b32_e32 v17, v173
	s_nop 1
	v_mfma_f32_16x16x32_bf16 v[50:53], v[14:17], v[18:21], 0
	v_mfma_f32_16x16x32_bf16 v[54:57], v[14:17], v[22:25], 0
	v_mfma_f32_16x16x32_bf16 v[58:61], v[14:17], v[34:37], 0
	v_mfma_f32_16x16x32_bf16 v[14:17], v[14:17], v[38:41], 0
	v_mov_b32_e32 v62, v174
	v_mov_b32_e32 v63, v175
	v_mov_b32_e32 v64, v176
	v_mov_b32_e32 v65, v177
	s_nop 1
	v_mfma_f32_16x16x32_bf16 v[70:73], v[62:65], v[18:21], 0
	v_mfma_f32_16x16x32_bf16 v[74:77], v[62:65], v[22:25], 0
	v_mfma_f32_16x16x32_bf16 v[78:81], v[62:65], v[34:37], 0
	v_mfma_f32_16x16x32_bf16 v[62:65], v[62:65], v[38:41], 0
	v_mov_b32_e32 v66, v178
	v_mov_b32_e32 v67, v179
	v_mov_b32_e32 v68, v180
	v_mov_b32_e32 v69, v181
	s_nop 1
	v_mfma_f32_16x16x32_bf16 v[18:21], v[66:69], v[18:21], 0
	v_mfma_f32_16x16x32_bf16 v[22:25], v[66:69], v[22:25], 0
	v_mfma_f32_16x16x32_bf16 v[34:37], v[66:69], v[34:37], 0
	v_mfma_f32_16x16x32_bf16 v[38:41], v[66:69], v[38:41], 0
	ds_read_b128 v[66:69], v104 offset:8256
	ds_read_b128 v[82:85], v105 offset:8256
	ds_read_b128 v[86:89], v106 offset:8256
	ds_read_b128 v[90:93], v13 offset:8256
	v_lshl_add_u64 v[98:99], v[8:9], 0, 64
	s_waitcnt lgkmcnt(3)
	v_mov_b32_e32 v94, v182
	v_mov_b32_e32 v95, v183
	v_mov_b32_e32 v96, v184
	v_mov_b32_e32 v97, v185
	s_nop 1
	v_mfma_f32_16x16x32_bf16 v[26:29], v[94:97], v[66:69], v[26:29]
	s_waitcnt lgkmcnt(2)
	v_mfma_f32_16x16x32_bf16 v[30:33], v[94:97], v[82:85], v[30:33]
	s_waitcnt lgkmcnt(1)
	v_mfma_f32_16x16x32_bf16 v[42:45], v[94:97], v[86:89], v[42:45]
	s_waitcnt lgkmcnt(0)
	v_mfma_f32_16x16x32_bf16 v[46:49], v[94:97], v[90:93], v[46:49]
	v_lshl_add_u64 v[94:95], v[98:99], 0, v[4:5]
	v_mov_b32_e32 v94, v186
	v_mov_b32_e32 v95, v187
	v_mov_b32_e32 v96, v188
	v_mov_b32_e32 v97, v189
	s_nop 1
	v_mfma_f32_16x16x32_bf16 v[50:53], v[94:97], v[66:69], v[50:53]
	v_mfma_f32_16x16x32_bf16 v[54:57], v[94:97], v[82:85], v[54:57]
	v_mfma_f32_16x16x32_bf16 v[58:61], v[94:97], v[86:89], v[58:61]
	v_mfma_f32_16x16x32_bf16 v[14:17], v[94:97], v[90:93], v[14:17]
	v_lshl_add_u64 v[94:95], v[98:99], 0, v[2:3]
	v_mov_b32_e32 v94, v190
	v_mov_b32_e32 v95, v191
	v_mov_b32_e32 v96, v192
	v_mov_b32_e32 v97, v193
	s_nop 1
	v_mfma_f32_16x16x32_bf16 v[70:73], v[94:97], v[66:69], v[70:73]
	v_mfma_f32_16x16x32_bf16 v[74:77], v[94:97], v[82:85], v[74:77]
	v_mfma_f32_16x16x32_bf16 v[78:81], v[94:97], v[86:89], v[78:81]
	v_mfma_f32_16x16x32_bf16 v[62:65], v[94:97], v[90:93], v[62:65]
	v_lshl_add_u64 v[94:95], v[98:99], 0, v[0:1]
	v_mov_b32_e32 v94, v194
	v_mov_b32_e32 v95, v195
	v_mov_b32_e32 v96, v196
	v_mov_b32_e32 v97, v197
	s_nop 1
	v_mfma_f32_16x16x32_bf16 v[18:21], v[94:97], v[66:69], v[18:21]
	v_mfma_f32_16x16x32_bf16 v[22:25], v[94:97], v[82:85], v[22:25]
	v_mfma_f32_16x16x32_bf16 v[34:37], v[94:97], v[86:89], v[34:37]
	v_mfma_f32_16x16x32_bf16 v[38:41], v[94:97], v[90:93], v[38:41]
	ds_read_b128 v[66:69], v104 offset:8320
	ds_read_b128 v[82:85], v105 offset:8320
	ds_read_b128 v[86:89], v106 offset:8320
	ds_read_b128 v[90:93], v13 offset:8320
	v_lshl_add_u64 v[102:103], v[8:9], 0, s[8:9]
	s_waitcnt lgkmcnt(1)
	v_mov_b32_e32 v94, v198
	v_mov_b32_e32 v95, v199
	v_mov_b32_e32 v96, v200
	v_mov_b32_e32 v97, v201
	s_nop 1
	v_mfma_f32_16x16x32_bf16 v[98:101], v[94:97], v[86:89], v[42:45]
	s_nop 2
	v_lshl_add_u64 v[42:43], v[102:103], 0, v[4:5]
	v_mfma_f32_16x16x32_bf16 v[26:29], v[94:97], v[66:69], v[26:29]
	v_mfma_f32_16x16x32_bf16 v[30:33], v[94:97], v[82:85], v[30:33]
	s_waitcnt lgkmcnt(0)
	v_mfma_f32_16x16x32_bf16 v[94:97], v[94:97], v[90:93], v[46:49]
	v_mov_b32_e32 v42, v202
	v_mov_b32_e32 v43, v203
	v_mov_b32_e32 v44, v204
	v_mov_b32_e32 v45, v205
	s_nop 1
	v_mfma_f32_16x16x32_bf16 v[48:51], v[42:45], v[66:69], v[50:53]
	v_mfma_f32_16x16x32_bf16 v[52:55], v[42:45], v[82:85], v[54:57]
	v_mfma_f32_16x16x32_bf16 v[56:59], v[42:45], v[86:89], v[58:61]
	v_mfma_f32_16x16x32_bf16 v[14:17], v[42:45], v[90:93], v[14:17]
	v_lshl_add_u64 v[42:43], v[102:103], 0, v[2:3]
	v_mov_b32_e32 v42, v230
	v_mov_b32_e32 v43, v231
	v_mov_b32_e32 v44, v232
	v_mov_b32_e32 v45, v233
	s_nop 1
	v_mfma_f32_16x16x32_bf16 v[70:73], v[42:45], v[66:69], v[70:73]
	v_mfma_f32_16x16x32_bf16 v[74:77], v[42:45], v[82:85], v[74:77]
	v_mfma_f32_16x16x32_bf16 v[78:81], v[42:45], v[86:89], v[78:81]
	v_mfma_f32_16x16x32_bf16 v[60:63], v[42:45], v[90:93], v[62:65]
	v_lshl_add_u64 v[42:43], v[102:103], 0, v[0:1]
	v_mov_b32_e32 v42, v234
	v_mov_b32_e32 v43, v235
	v_mov_b32_e32 v44, v236
	v_mov_b32_e32 v45, v237
	s_nop 1
	v_mfma_f32_16x16x32_bf16 v[18:21], v[42:45], v[66:69], v[18:21]
	v_mfma_f32_16x16x32_bf16 v[22:25], v[42:45], v[82:85], v[22:25]
	v_mfma_f32_16x16x32_bf16 v[34:37], v[42:45], v[86:89], v[34:37]
	v_mfma_f32_16x16x32_bf16 v[38:41], v[42:45], v[90:93], v[38:41]
	s_mov_b64 s[30:31], 0xc0
	ds_read_b128 v[64:67], v104 offset:8384
	ds_read_b128 v[82:85], v105 offset:8384
	ds_read_b128 v[86:89], v106 offset:8384
	ds_read_b128 v[90:93], v13 offset:8384
	v_lshl_add_u64 v[42:43], v[8:9], 0, s[30:31]
	v_lshl_add_u64 v[4:5], v[42:43], 0, v[4:5]
	v_lshl_add_u64 v[2:3], v[42:43], 0, v[2:3]
	v_lshl_add_u64 v[0:1], v[42:43], 0, v[0:1]
	s_waitcnt lgkmcnt(3)
	v_mov_b32_e32 v6, v238
	v_mov_b32_e32 v7, v239
	v_mov_b32_e32 v8, v240
	v_mov_b32_e32 v9, v241
	s_nop 1
	v_mfma_f32_16x16x32_bf16 v[44:47], v[6:9], v[64:67], v[26:29]
	s_waitcnt lgkmcnt(2)
	v_mfma_f32_16x16x32_bf16 v[26:29], v[6:9], v[82:85], v[30:33]
	s_nop 2
	s_waitcnt lgkmcnt(1)
	v_mfma_f32_16x16x32_bf16 v[98:101], v[6:9], v[86:89], v[98:101]
	s_waitcnt lgkmcnt(0)
	v_mfma_f32_16x16x32_bf16 v[6:9], v[6:9], v[90:93], v[94:97]
	v_mov_b32_e32 v30, v242
	v_mov_b32_e32 v31, v243
	v_mov_b32_e32 v32, v244
	v_mov_b32_e32 v33, v245
	s_nop 1
	v_mfma_f32_16x16x32_bf16 v[104:107], v[30:33], v[64:67], v[48:51]
	v_mfma_f32_16x16x32_bf16 v[48:51], v[30:33], v[82:85], v[52:55]
	v_mfma_f32_16x16x32_bf16 v[52:55], v[30:33], v[86:89], v[56:59]
	v_mfma_f32_16x16x32_bf16 v[14:17], v[30:33], v[90:93], v[14:17]
	v_mov_b32_e32 v2, v246
	v_mov_b32_e32 v3, v247
	v_mov_b32_e32 v4, v248
	v_mov_b32_e32 v5, v249
	s_nop 1
	v_mfma_f32_16x16x32_bf16 v[108:111], v[2:5], v[64:67], v[70:73]
	v_mfma_f32_16x16x32_bf16 v[30:33], v[2:5], v[82:85], v[74:77]
	v_mfma_f32_16x16x32_bf16 v[56:59], v[2:5], v[86:89], v[78:81]
	v_mfma_f32_16x16x32_bf16 v[60:63], v[2:5], v[90:93], v[60:63]
	v_mov_b32_e32 v0, v250
	v_mov_b32_e32 v1, v251
	v_mov_b32_e32 v2, v252
	v_mov_b32_e32 v3, v253
	s_nop 1
	v_mfma_f32_16x16x32_bf16 v[112:115], v[0:3], v[64:67], v[18:21]
	v_mfma_f32_16x16x32_bf16 v[18:21], v[0:3], v[82:85], v[22:25]
	v_mfma_f32_16x16x32_bf16 v[22:25], v[0:3], v[86:89], v[34:37]
	v_mfma_f32_16x16x32_bf16 v[64:67], v[0:3], v[90:93], v[38:41]
	s_lshl_b32 s17, s24, 2
	s_add_i32 s17, s17, 0
	v_add_u32_e32 v126, s17, v12
	v_add_u32_e32 v0, 0x800, v126
	ds_read2_b32 v[96:97], v0 offset1:16
	ds_read2_b32 v[116:117], v0 offset0:32 offset1:48
	v_cmp_lt_u32_e32 vcc, v162, v124
	v_or_b32_e32 v141, 2, v162
	v_or_b32_e32 v140, 3, v162
	s_waitcnt lgkmcnt(1)
	v_mul_f32_e32 v0, 0x3fb8aa3b, v97
	v_exp_f32_e32 v4, v0
	s_waitcnt lgkmcnt(0)
	v_mul_f32_e32 v0, 0x3fb8aa3b, v116
	v_exp_f32_e32 v12, v0
	v_or_b32_e32 v150, 4, v162
	v_pk_mul_f32 v[42:43], v[28:29], v[4:5] op_sel_hi:[1,0]
	v_pk_mul_f32 v[40:41], v[26:27], v[4:5] op_sel_hi:[1,0]
	v_pk_mul_f32 v[38:39], v[50:51], v[4:5] op_sel_hi:[1,0]
	v_pk_mul_f32 v[36:37], v[48:49], v[4:5] op_sel_hi:[1,0]
	v_pk_mul_f32 v[2:3], v[32:33], v[4:5] op_sel_hi:[1,0]
	v_pk_mul_f32 v[0:1], v[30:31], v[4:5] op_sel_hi:[1,0]
	v_pk_mul_f32 v[30:31], v[20:21], v[4:5] op_sel_hi:[1,0]
	v_pk_mul_f32 v[28:29], v[18:19], v[4:5] op_sel_hi:[1,0]
	v_mul_f32_e32 v4, 0x3fb8aa3b, v117
	v_exp_f32_e32 v4, v4
	v_mul_f32_e32 v20, 0x3fb8aa3b, v96
	v_pk_mul_f32 v[72:73], v[52:53], v[12:13] op_sel_hi:[1,0]
	v_exp_f32_e32 v52, v20
	v_pk_mul_f32 v[78:79], v[58:59], v[12:13] op_sel_hi:[1,0]
	v_pk_mul_f32 v[76:77], v[56:57], v[12:13] op_sel_hi:[1,0]
	v_pk_mul_f32 v[50:51], v[8:9], v[4:5] op_sel_hi:[1,0]
	v_pk_mul_f32 v[48:49], v[6:7], v[4:5] op_sel_hi:[1,0]
	v_pk_mul_f32 v[58:59], v[16:17], v[4:5] op_sel_hi:[1,0]
	v_pk_mul_f32 v[56:57], v[14:15], v[4:5] op_sel_hi:[1,0]
	v_pk_mul_f32 v[62:63], v[62:63], v[4:5] op_sel_hi:[1,0]
	v_pk_mul_f32 v[60:61], v[60:61], v[4:5] op_sel_hi:[1,0]
	v_pk_mul_f32 v[66:67], v[66:67], v[4:5] op_sel_hi:[1,0]
	v_pk_mul_f32 v[64:65], v[64:65], v[4:5] op_sel_hi:[1,0]
	v_or_b32_e32 v4, s24, v124
	v_lshlrev_b32_e32 v5, 5, v10
	v_mul_lo_u32 v4, v4, s90
	v_add_u32_e32 v131, s17, v5
	v_add3_u32 v136, s34, v11, v4
	v_pk_mul_f32 v[70:71], v[100:101], v[12:13] op_sel_hi:[1,0]
	v_pk_mul_f32 v[68:69], v[98:99], v[12:13] op_sel_hi:[1,0]
	v_pk_mul_f32 v[74:75], v[54:55], v[12:13] op_sel_hi:[1,0]
	v_pk_mul_f32 v[82:83], v[24:25], v[12:13] op_sel_hi:[1,0]
	v_pk_mul_f32 v[80:81], v[22:23], v[12:13] op_sel_hi:[1,0]
	v_add_u32_e32 v118, 0, v5
	ds_read_b128 v[16:19], v136
	ds_read_b128 v[12:15], v136 offset:2304
	ds_read_b128 v[8:11], v136 offset:4608
	ds_read_b128 v[4:7], v136 offset:6912
	ds_read_b128 v[100:103], v131 offset:2048
	ds_read_b128 v[92:95], v131 offset:2064
	ds_read_b128 v[88:91], v131
	ds_read_b128 v[84:87], v131 offset:16
	v_pk_mul_f32 v[22:23], v[114:115], v[52:53] op_sel_hi:[1,0]
	v_pk_mul_f32 v[20:21], v[112:113], v[52:53] op_sel_hi:[1,0]
	v_pk_mul_f32 v[26:27], v[110:111], v[52:53] op_sel_hi:[1,0]
	v_pk_mul_f32 v[24:25], v[108:109], v[52:53] op_sel_hi:[1,0]
	v_pk_mul_f32 v[34:35], v[106:107], v[52:53] op_sel_hi:[1,0]
	v_pk_mul_f32 v[32:33], v[104:105], v[52:53] op_sel_hi:[1,0]
	v_pk_mul_f32 v[54:55], v[46:47], v[52:53] op_sel_hi:[1,0]
	v_pk_mul_f32 v[52:53], v[44:45], v[52:53] op_sel_hi:[1,0]
	v_or_b32_e32 v44, s16, v124
	v_mad_u64_u32 v[98:99], s[30:31], v44, s79, v[118:119]
	v_add_u32_e32 v44, 0xa400, v98
	s_waitcnt lgkmcnt(3)
	v_sub_f32_e32 v99, v96, v100
	ds_read2_b64 v[44:47], v44 offset1:1
	v_mul_f32_e32 v99, 0x3fb8aa3b, v99
	v_sub_f32_e32 v104, v96, v101
	v_add_u32_e32 v98, 0xa410, v98
	v_exp_f32_e32 v99, v99
	v_mul_f32_e32 v104, 0x3fb8aa3b, v104
	v_exp_f32_e32 v108, v104
	ds_read2_b64 v[104:107], v98 offset1:1
	s_waitcnt lgkmcnt(4)
	v_sub_f32_e32 v98, v96, v92
	v_mul_f32_e32 v98, 0x3fb8aa3b, v98
	v_exp_f32_e32 v122, v98
	v_sub_f32_e32 v98, v96, v93
	s_waitcnt lgkmcnt(1)
	v_mul_f32_e32 v44, v44, v99
	v_mul_f32_e32 v98, 0x3fb8aa3b, v98
	v_mul_f32_e32 v160, v88, v44
	v_mul_f32_e32 v44, v45, v108
	v_exp_f32_e32 v123, v98
	v_sub_f32_e32 v98, v96, v94
	v_mul_f32_e32 v44, v89, v44
	v_mul_f32_e32 v98, 0x3fb8aa3b, v98
	v_cndmask_b32_e32 v161, 0, v44, vcc
	v_sub_f32_e32 v44, v96, v102
	v_sub_f32_e32 v45, v96, v103
	v_exp_f32_e32 v120, v98
	v_sub_f32_e32 v96, v96, v95
	v_or_b32_e32 v98, s16, v130
	v_mul_f32_e32 v96, 0x3fb8aa3b, v96
	v_mad_u64_u32 v[98:99], s[30:31], v98, s79, v[118:119]
	v_add_u32_e32 v99, 0xa400, v98
	v_exp_f32_e32 v121, v96
	v_add_u32_e32 v96, 0xa410, v98
	ds_read2_b64 v[108:111], v99 offset1:1
	ds_read2_b64 v[112:115], v96 offset1:1
	v_sub_f32_e32 v99, v97, v100
	v_mul_f32_e32 v99, 0x3fb8aa3b, v99
	v_exp_f32_e32 v99, v99
	v_sub_f32_e32 v98, v97, v101
	v_mul_f32_e32 v98, 0x3fb8aa3b, v98
	v_exp_f32_e32 v98, v98
	s_waitcnt lgkmcnt(1)
	v_mul_f32_e32 v96, v108, v99
	v_mul_f32_e32 v96, v88, v96
	v_cmp_le_u32_e32 vcc, v162, v130
	v_mul_f32_e32 v44, 0x3fb8aa3b, v44
	v_mul_f32_e32 v45, 0x3fb8aa3b, v45
	v_cndmask_b32_e32 v108, 0, v96, vcc
	v_mul_f32_e32 v96, v109, v98
	v_mul_f32_e32 v96, v89, v96
	v_cmp_lt_u32_e32 vcc, v162, v130
	v_exp_f32_e32 v44, v44
	v_exp_f32_e32 v45, v45
	v_cndmask_b32_e32 v109, 0, v96, vcc
	v_sub_f32_e32 v96, v97, v102
	v_mul_f32_e32 v96, 0x3fb8aa3b, v96
	v_exp_f32_e32 v98, v96
	v_sub_f32_e32 v96, v97, v103
	v_mul_f32_e32 v96, 0x3fb8aa3b, v96
	v_exp_f32_e32 v99, v96
	v_pk_mul_f32 v[138:139], v[46:47], v[44:45]
	v_sub_f32_e32 v46, v97, v92
	v_sub_f32_e32 v47, v97, v93
	v_mul_f32_e32 v46, 0x3fb8aa3b, v46
	v_mul_f32_e32 v47, 0x3fb8aa3b, v47
	v_exp_f32_e32 v46, v46
	v_exp_f32_e32 v47, v47
	v_pk_mul_f32 v[44:45], v[110:111], v[98:99]
	v_sub_f32_e32 v96, v97, v94
	v_sub_f32_e32 v97, v97, v95
	v_pk_mul_f32 v[44:45], v[90:91], v[44:45]
	v_mul_f32_e32 v96, 0x3fb8aa3b, v96
	v_mul_f32_e32 v97, 0x3fb8aa3b, v97
	v_exp_f32_e32 v96, v96
	v_exp_f32_e32 v97, v97
	v_cvt_pk_bf16_f32 v44, v44, v45
	v_cmp_le_u32_e32 vcc, v141, v130
	s_waitcnt lgkmcnt(0)
	v_pk_mul_f32 v[46:47], v[46:47], v[112:113]
	v_or_b32_e32 v156, 5, v162
	v_cndmask_b32_e32 v45, 0, v44, vcc
	v_lshrrev_b32_e32 v44, 16, v44
	v_cmp_le_u32_e32 vcc, v140, v130
	v_pk_mul_f32 v[46:47], v[84:85], v[46:47]
	v_pk_mul_f32 v[96:97], v[96:97], v[114:115]
	v_cndmask_b32_e32 v44, 0, v44, vcc
	v_perm_b32 v133, v44, v45, s91
	v_cvt_pk_bf16_f32 v44, v46, v47
	v_cmp_le_u32_e32 vcc, v150, v130
	v_or_b32_e32 v158, 6, v162
	v_pk_mul_f32 v[96:97], v[86:87], v[96:97]
	v_cndmask_b32_e32 v45, 0, v44, vcc
	v_lshrrev_b32_e32 v44, 16, v44
	v_cmp_le_u32_e32 vcc, v156, v130
	v_or_b32_e32 v157, 7, v162
	v_cvt_pk_bf16_f32 v132, v108, v109
	v_cndmask_b32_e32 v44, 0, v44, vcc
	v_perm_b32 v134, v44, v45, s91
	v_cvt_pk_bf16_f32 v44, v96, v97
	v_cmp_le_u32_e32 vcc, v158, v130
	ds_read_b128 v[108:111], v136 offset:64
	ds_read_b128 v[112:115], v136 offset:2368
	v_cndmask_b32_e32 v45, 0, v44, vcc
	v_lshrrev_b32_e32 v44, 16, v44
	v_cmp_le_u32_e32 vcc, v157, v130
	s_nop 1
	v_cndmask_b32_e32 v44, 0, v44, vcc
	v_perm_b32 v135, v44, v45, s91
	v_cmp_le_u32_e32 vcc, v141, v124
	s_nop 0
	v_mfma_f32_16x16x32_bf16 v[44:47], v[16:19], v[132:135], v[40:43]
	s_nop 2
	v_mul_f32_e64 v40, v90, v138
	v_mul_f32_e64 v41, v91, v139
	v_mfma_f32_16x16x32_bf16 v[28:31], v[4:7], v[132:135], v[28:31]
	v_cvt_pk_bf16_f32 v96, v40, v41
	v_cndmask_b32_e32 v138, 0, v96, vcc
	v_lshrrev_b32_e32 v139, 16, v96
	v_cmp_le_u32_e32 vcc, v140, v124
	v_mfma_f32_16x16x32_bf16 v[40:43], v[12:15], v[132:135], v[36:39]
	ds_read_b128 v[96:99], v136 offset:4672
	v_mfma_f32_16x16x32_bf16 v[36:39], v[8:11], v[132:135], v[0:3]
	v_or_b32_e32 v132, s16, v129
	v_mad_u64_u32 v[154:155], s[30:31], v132, s79, v[118:119]
	s_nop 0
	v_cndmask_b32_e32 v0, 0, v139, vcc
	v_perm_b32 v139, v0, v138, s91
	v_sub_f32_e32 v138, v116, v100
	v_mul_f32_e32 v138, 0x3fb8aa3b, v138
	v_add_u32_e32 v132, 0xa400, v154
	v_exp_f32_e32 v144, v138
	v_sub_f32_e32 v138, v116, v101
	ds_read2_b64 v[132:135], v132 offset1:1
	v_mul_f32_e32 v138, 0x3fb8aa3b, v138
	v_exp_f32_e32 v145, v138
	v_sub_f32_e32 v138, v116, v102
	ds_read_b128 v[0:3], v136 offset:6976
	v_add_u32_e32 v136, 0xa410, v154
	v_mul_f32_e32 v138, 0x3fb8aa3b, v138
	v_exp_f32_e32 v146, v138
	v_sub_f32_e32 v138, v116, v103
	ds_read2_b64 v[140:143], v136 offset1:1
	v_sub_f32_e32 v136, v116, v92
	v_mul_f32_e32 v138, 0x3fb8aa3b, v138
	v_mul_f32_e32 v136, 0x3fb8aa3b, v136
	v_exp_f32_e32 v147, v138
	s_waitcnt lgkmcnt(2)
	v_pk_mul_f32 v[132:133], v[132:133], v[144:145]
	v_exp_f32_e32 v144, v136
	v_sub_f32_e32 v136, v116, v93
	v_mul_f32_e32 v136, 0x3fb8aa3b, v136
	v_exp_f32_e32 v145, v136
	v_sub_f32_e32 v136, v116, v94
	v_mul_f32_e32 v136, 0x3fb8aa3b, v136
	v_pk_mul_f32 v[134:135], v[134:135], v[146:147]
	v_exp_f32_e32 v146, v136
	v_sub_f32_e32 v136, v116, v95
	v_mul_f32_e32 v136, 0x3fb8aa3b, v136
	v_exp_f32_e32 v147, v136
	s_waitcnt lgkmcnt(0)
	v_pk_mul_f32 v[140:141], v[144:145], v[140:141]
	v_pk_mul_f32 v[132:133], v[88:89], v[132:133]
	v_pk_mul_f32 v[134:135], v[90:91], v[134:135]
	v_pk_mul_f32 v[142:143], v[146:147], v[142:143]
	v_pk_mul_f32 v[140:141], v[84:85], v[140:141]
	v_pk_mul_f32 v[142:143], v[86:87], v[142:143]
	v_cvt_pk_bf16_f32 v132, v132, v133
	v_cvt_pk_bf16_f32 v133, v134, v135
	v_cvt_pk_bf16_f32 v134, v140, v141
	v_cvt_pk_bf16_f32 v135, v142, v143
	v_cmp_le_u32_e32 vcc, v150, v124
	s_nop 0
	v_mfma_f32_16x16x32_bf16 v[142:145], v[16:19], v[132:135], v[68:71]
	s_nop 2
	v_mul_f32_e64 v68, v122, v104
	v_mul_f32_e64 v69, v123, v105
	v_mfma_f32_16x16x32_bf16 v[146:149], v[12:15], v[132:135], v[72:75]
	v_mul_f32_e64 v68, v84, v68
	v_mul_f32_e64 v69, v85, v69
	v_cvt_pk_bf16_f32 v68, v68, v69
	v_sub_f32_e32 v73, v117, v100
	v_mul_f32_e32 v73, 0x3fb8aa3b, v73
	v_cndmask_b32_e32 v69, 0, v68, vcc
	v_lshrrev_b32_e32 v68, 16, v68
	v_mfma_f32_16x16x32_bf16 v[150:153], v[8:11], v[132:135], v[76:79]
	v_cmp_le_u32_e32 vcc, v156, v124
	s_nop 1
	v_exp_f32_e32 v76, v73
	v_sub_f32_e32 v73, v117, v101
	v_cndmask_b32_e32 v68, 0, v68, vcc
	v_mul_f32_e32 v73, 0x3fb8aa3b, v73
	v_perm_b32 v140, v68, v69, s91
	v_or_b32_e32 v68, s16, v127
	v_exp_f32_e32 v77, v73
	v_sub_f32_e32 v73, v117, v102
	v_mad_u64_u32 v[122:123], s[16:17], v68, s79, v[118:119]
	v_mul_f32_e32 v73, 0x3fb8aa3b, v73
	v_add_u32_e32 v68, 0xa400, v122
	v_exp_f32_e32 v78, v73
	v_sub_f32_e32 v73, v117, v103
	ds_read2_b64 v[68:71], v68 offset1:1
	v_mul_f32_e32 v73, 0x3fb8aa3b, v73
	v_exp_f32_e32 v79, v73
	v_add_u32_e32 v72, 0xa410, v122
	ds_read2_b64 v[72:75], v72 offset1:1
	s_waitcnt lgkmcnt(1)
	v_pk_mul_f32 v[68:69], v[68:69], v[76:77]
	v_pk_mul_f32 v[70:71], v[70:71], v[78:79]
	v_sub_f32_e32 v76, v117, v92
	v_sub_f32_e32 v77, v117, v93
	v_sub_f32_e32 v78, v117, v94
	v_sub_f32_e32 v79, v117, v95
	v_mul_f32_e32 v76, 0x3fb8aa3b, v76
	v_mul_f32_e32 v77, 0x3fb8aa3b, v77
	v_mul_f32_e32 v78, 0x3fb8aa3b, v78
	v_mul_f32_e32 v79, 0x3fb8aa3b, v79
	v_exp_f32_e32 v76, v76
	v_exp_f32_e32 v77, v77
	v_exp_f32_e32 v78, v78
	v_exp_f32_e32 v79, v79
	v_pk_mul_f32 v[68:69], v[88:89], v[68:69]
	s_waitcnt lgkmcnt(0)
	v_pk_mul_f32 v[72:73], v[76:77], v[72:73]
	v_pk_mul_f32 v[70:71], v[90:91], v[70:71]
	v_pk_mul_f32 v[74:75], v[78:79], v[74:75]
	v_pk_mul_f32 v[72:73], v[84:85], v[72:73]
	v_pk_mul_f32 v[74:75], v[86:87], v[74:75]
	v_cvt_pk_bf16_f32 v68, v68, v69
	v_cvt_pk_bf16_f32 v69, v70, v71
	v_cvt_pk_bf16_f32 v70, v72, v73
	v_cvt_pk_bf16_f32 v71, v74, v75
	v_mfma_f32_16x16x32_bf16 v[132:135], v[4:7], v[132:135], v[80:83]
	v_cmp_le_u32_e32 vcc, v158, v124
	v_or_b32_e32 v118, 32, v162
	s_mov_b64 s[16:17], s[44:45]
	v_mfma_f32_16x16x32_bf16 v[76:79], v[16:19], v[68:71], v[48:51]
	s_nop 2
	v_mul_f32_e64 v48, v120, v106
	v_mul_f32_e64 v49, v121, v107
	v_mfma_f32_16x16x32_bf16 v[80:83], v[12:15], v[68:71], v[56:59]
	v_mul_f32_e64 v48, v86, v48
	v_mul_f32_e64 v49, v87, v49
	v_cvt_pk_bf16_f32 v48, v48, v49
	v_mfma_f32_16x16x32_bf16 v[72:75], v[8:11], v[68:71], v[60:63]
	s_nop 2
	ds_read_b128 v[58:61], v131 offset:2176
	ds_read_b128 v[84:87], v131 offset:2192
	ds_read_b128 v[88:91], v131 offset:128
	ds_read_b128 v[92:95], v131 offset:144
	v_add_u32_e32 v56, 0xa480, v154
	v_add_u32_e32 v57, 0xa490, v154
	ds_read2_b64 v[100:103], v56 offset1:1
	ds_read2_b64 v[104:107], v57 offset1:1
	s_waitcnt lgkmcnt(5)
	v_sub_f32_e32 v56, v116, v58
	v_mul_f32_e32 v56, 0x3fb8aa3b, v56
	v_exp_f32_e32 v62, v56
	v_sub_f32_e32 v56, v116, v59
	v_mul_f32_e32 v56, 0x3fb8aa3b, v56
	v_exp_f32_e32 v63, v56
	v_sub_f32_e32 v56, v116, v60
	v_mul_f32_e32 v56, 0x3fb8aa3b, v56
	v_exp_f32_e32 v154, v56
	v_sub_f32_e32 v56, v116, v61
	v_mul_f32_e32 v56, 0x3fb8aa3b, v56
	v_exp_f32_e32 v155, v56
	s_waitcnt lgkmcnt(4)
	v_sub_f32_e32 v56, v116, v84
	v_cndmask_b32_e32 v49, 0, v48, vcc
	v_lshrrev_b32_e32 v48, 16, v48
	v_cmp_le_u32_e32 vcc, v157, v124
	v_mul_f32_e32 v56, 0x3fb8aa3b, v56
	v_exp_f32_e32 v156, v56
	v_cndmask_b32_e32 v48, 0, v48, vcc
	v_sub_f32_e32 v56, v116, v85
	v_cmp_le_u32_e32 vcc, v162, v124
	v_perm_b32 v141, v48, v49, s91
	v_mfma_f32_16x16x32_bf16 v[48:51], v[4:7], v[68:71], v[64:67]
	v_mul_f32_e32 v56, 0x3fb8aa3b, v56
	v_exp_f32_e32 v157, v56
	v_sub_f32_e32 v56, v116, v86
	v_cndmask_b32_e32 v64, 0, v160, vcc
	v_cvt_pk_bf16_f32 v138, v64, v161
	v_mul_f32_e32 v56, 0x3fb8aa3b, v56
	v_exp_f32_e32 v158, v56
	v_mfma_f32_16x16x32_bf16 v[68:71], v[16:19], v[138:141], v[52:55]
	v_sub_f32_e32 v56, v116, v87
	v_mul_f32_e32 v56, 0x3fb8aa3b, v56
	v_exp_f32_e32 v159, v56
	v_sub_f32_e32 v52, v117, v58
	v_mul_f32_e32 v52, 0x3fb8aa3b, v52
	v_mfma_f32_16x16x32_bf16 v[64:67], v[12:15], v[138:141], v[32:35]
	v_exp_f32_e32 v12, v52
	v_sub_f32_e32 v13, v117, v59
	v_add_u32_e32 v56, 0xa480, v122
	v_mfma_f32_16x16x32_bf16 v[52:55], v[4:7], v[138:141], v[20:23]
	s_waitcnt lgkmcnt(1)
	v_pk_mul_f32 v[4:5], v[62:63], v[100:101]
	v_mul_f32_e32 v13, 0x3fb8aa3b, v13
	v_pk_mul_f32 v[4:5], v[88:89], v[4:5]
	v_add_u32_e32 v57, 0xa490, v122
	ds_read2_b64 v[16:19], v56 offset1:1
	ds_read2_b64 v[120:123], v57 offset1:1
	v_exp_f32_e32 v13, v13
	v_or_b32_e32 v116, 33, v162
	v_cvt_pk_bf16_f32 v4, v4, v5
	v_cndmask_b32_e32 v5, 0, v4, vcc
	v_lshrrev_b32_e32 v4, 16, v4
	v_cmp_le_u32_e32 vcc, v116, v129
	s_waitcnt lgkmcnt(1)
	v_pk_mul_f32 v[6:7], v[12:13], v[16:17]
	v_mfma_f32_16x16x32_bf16 v[56:59], v[8:11], v[138:141], v[24:27]
	v_cndmask_b32_e32 v4, 0, v4, vcc
	v_perm_b32 v4, v4, v5, s91
	v_sub_f32_e32 v5, v117, v60
	v_mul_f32_e32 v5, 0x3fb8aa3b, v5
	v_pk_mul_f32 v[8:9], v[88:89], v[6:7]
	v_exp_f32_e32 v6, v5
	v_sub_f32_e32 v5, v117, v61
	v_mul_f32_e32 v5, 0x3fb8aa3b, v5
	v_exp_f32_e32 v7, v5
	v_pk_mul_f32 v[10:11], v[154:155], v[102:103]
	v_or_b32_e32 v62, 34, v162
	v_pk_mul_f32 v[10:11], v[90:91], v[10:11]
	v_or_b32_e32 v61, 35, v162
	v_cvt_pk_bf16_f32 v5, v10, v11
	v_cmp_le_u32_e32 vcc, v62, v129
	v_pk_mul_f32 v[6:7], v[6:7], v[18:19]
	v_or_b32_e32 v63, 37, v162
	v_cndmask_b32_e32 v10, 0, v5, vcc
	v_lshrrev_b32_e32 v5, 16, v5
	v_cmp_le_u32_e32 vcc, v61, v129
	v_pk_mul_f32 v[14:15], v[158:159], v[106:107]
	s_add_u32 s16, s16, s26
	v_cndmask_b32_e32 v5, 0, v5, vcc
	v_perm_b32 v5, v5, v10, s91
	v_pk_mul_f32 v[10:11], v[90:91], v[6:7]
	v_sub_f32_e32 v6, v117, v84
	v_mul_f32_e32 v6, 0x3fb8aa3b, v6
	v_exp_f32_e32 v12, v6
	v_sub_f32_e32 v6, v117, v85
	v_mul_f32_e32 v13, 0x3fb8aa3b, v6
	v_pk_mul_f32 v[6:7], v[156:157], v[104:105]
	v_or_b32_e32 v85, 36, v162
	v_pk_mul_f32 v[6:7], v[92:93], v[6:7]
	v_cmp_le_u32_e32 vcc, v85, v129
	v_cvt_pk_bf16_f32 v6, v6, v7
	v_or_b32_e32 v91, 38, v162
	v_cndmask_b32_e32 v7, 0, v6, vcc
	v_lshrrev_b32_e32 v6, 16, v6
	v_cmp_le_u32_e32 vcc, v63, v129
	v_pk_mul_f32 v[14:15], v[94:95], v[14:15]
	v_or_b32_e32 v90, 39, v162
	v_cndmask_b32_e32 v6, 0, v6, vcc
	v_perm_b32 v6, v6, v7, s91
	v_cvt_pk_bf16_f32 v7, v14, v15
	v_cmp_le_u32_e32 vcc, v91, v129
	v_or_b32_e32 v84, s67, v124
	s_addc_u32 s17, s17, s27
	v_cndmask_b32_e32 v14, 0, v7, vcc
	v_lshrrev_b32_e32 v7, 16, v7
	v_cmp_le_u32_e32 vcc, v90, v129
	s_ashr_i32 s25, s24, 31
	v_exp_f32_e32 v13, v13
	v_cndmask_b32_e32 v7, 0, v7, vcc
	v_perm_b32 v7, v7, v14, s91
	v_cmp_le_u32_e32 vcc, v118, v127
	v_sub_f32_e32 v14, v117, v86
	v_mfma_f32_16x16x32_bf16 v[32:35], v[108:111], v[4:7], v[142:145]
	v_sub_f32_e32 v15, v117, v87
	v_mul_f32_e32 v14, 0x3fb8aa3b, v14
	v_mul_f32_e32 v15, 0x3fb8aa3b, v15
	v_mfma_f32_16x16x32_bf16 v[24:27], v[112:115], v[4:7], v[146:149]
	v_exp_f32_e32 v14, v14
	v_exp_f32_e32 v15, v15
	s_waitcnt lgkmcnt(0)
	v_pk_mul_f32 v[12:13], v[12:13], v[120:121]
	v_mfma_f32_16x16x32_bf16 v[20:23], v[96:99], v[4:7], v[150:153]
	v_mul_f32_e64 v12, v92, v12
	v_mul_f32_e64 v13, v93, v13
	v_mfma_f32_16x16x32_bf16 v[16:19], v[0:3], v[4:7], v[132:135]
	v_cvt_pk_bf16_f32 v6, v8, v9
	v_cndmask_b32_e32 v7, 0, v6, vcc
	v_lshrrev_b32_e32 v6, 16, v6
	v_cmp_le_u32_e32 vcc, v116, v127
	v_pk_mul_f32 v[4:5], v[14:15], v[122:123]
	s_nop 0
	v_cndmask_b32_e32 v6, 0, v6, vcc
	v_perm_b32 v60, v6, v7, s91
	v_mov_b64_e32 v[6:7], s[20:21]
	v_mad_i64_i32 v[6:7], s[26:27], v84, s76, v[6:7]
	v_lshl_add_u64 v[6:7], s[24:25], 1, v[6:7]
	v_lshl_add_u64 v[86:87], v[6:7], 0, v[162:163]
	global_load_dwordx2 v[88:89], v[86:87], off offset:1536
	v_cvt_pk_bf16_f32 v6, v10, v11
	v_cmp_le_u32_e32 vcc, v62, v127
	v_pk_mul_f32 v[4:5], v[94:95], v[4:5]
	s_nop 0
	v_cndmask_b32_e32 v7, 0, v6, vcc
	v_lshrrev_b32_e32 v6, 16, v6
	v_cmp_le_u32_e32 vcc, v61, v127
	v_cvt_pk_bf16_f32 v4, v4, v5
	s_nop 0
	v_cndmask_b32_e32 v6, 0, v6, vcc
	v_perm_b32 v61, v6, v7, s91
	v_cvt_pk_bf16_f32 v6, v12, v13
	v_cmp_le_u32_e32 vcc, v85, v127
	v_xor_b32_e32 v85, 64, v128
	s_nop 0
	v_cndmask_b32_e32 v7, 0, v6, vcc
	v_lshrrev_b32_e32 v6, 16, v6
	v_cmp_le_u32_e32 vcc, v63, v127
	s_nop 1
	v_cndmask_b32_e32 v6, 0, v6, vcc
	v_cmp_le_u32_e32 vcc, v91, v127
	v_perm_b32 v62, v6, v7, s91
	s_nop 0
	v_cndmask_b32_e32 v5, 0, v4, vcc
	v_lshrrev_b32_e32 v4, 16, v4
	v_cmp_le_u32_e32 vcc, v90, v127
	s_nop 1
	v_cndmask_b32_e32 v4, 0, v4, vcc
	v_perm_b32 v63, v4, v5, s91
	v_mov_b64_e32 v[4:5], s[16:17]
	s_nop 0
	v_mfma_f32_16x16x32_bf16 v[12:15], v[108:111], v[60:63], v[76:79]
	s_nop 2
	flat_load_dword v76, v[4:5]
	global_load_dwordx2 v[78:79], v[86:87], off offset:1568
	v_mfma_f32_16x16x32_bf16 v[4:7], v[96:99], v[60:63], v[72:75]
	s_nop 2
	global_load_dwordx2 v[72:73], v[86:87], off offset:1600
	global_load_dwordx2 v[74:75], v[86:87], off offset:1632
	v_or_b32_e32 v96, s24, v125
	v_or_b32_e32 v87, 16, v96
	v_mfma_f32_16x16x32_bf16 v[8:11], v[112:115], v[60:63], v[80:83]
	v_lshl_add_u32 v77, v124, 1, s34
	v_mul_lo_u32 v93, v96, s90
	v_mul_lo_u32 v92, v87, s90
	v_add_u32_e32 v86, v77, v93
	v_add_u32_e32 v87, v77, v92
	v_mfma_f32_16x16x32_bf16 v[0:3], v[0:3], v[60:63], v[48:51]
	s_waitcnt vmcnt(0)
	v_lshlrev_b32_e32 v80, 16, v88
	v_and_b32_e32 v81, 0xffff0000, v88
	v_mul_f32_e32 v82, 0xbfb8aa3b, v80
	v_mul_f32_e32 v83, 0xbfb8aa3b, v81
	v_exp_f32_e32 v82, v82
	v_exp_f32_e32 v83, v83
	ds_read_u16 v88, v86
	ds_read_u16 v90, v86 offset:144
	ds_read_u16 v91, v86 offset:288
	ds_read_u16 v94, v86 offset:432
	ds_read_u16 v95, v87
	ds_read_u16 v97, v87 offset:144
	ds_read_u16 v98, v87 offset:288
	ds_read_u16 v99, v87 offset:432
	s_waitcnt lgkmcnt(0)
	v_lshlrev_b32_e32 v87, 16, v90
	v_add_f32_e32 v82, 1.0, v82
	v_add_f32_e32 v83, 1.0, v83
	v_rcp_f32_e32 v82, v82
	v_rcp_f32_e32 v83, v83
	v_lshlrev_b32_e32 v86, 16, v88
	v_lshlrev_b32_e32 v88, 16, v91
	v_lshlrev_b32_e32 v91, 16, v97
	v_pk_mul_f32 v[80:81], v[82:83], v[80:81]
	v_lshlrev_b32_e32 v90, 16, v95
	v_pk_fma_f32 v[68:69], v[76:77], v[86:87], v[68:69] op_sel_hi:[0,1,1]
	v_pk_mul_f32 v[68:69], v[68:69], v[80:81]
	v_lshlrev_b32_e32 v80, 16, v89
	v_and_b32_e32 v81, 0xffff0000, v89
	v_mul_f32_e32 v82, 0xbfb8aa3b, v80
	v_exp_f32_e32 v86, v82
	v_mul_f32_e32 v82, 0xbfb8aa3b, v81
	v_exp_f32_e32 v87, v82
	v_lshlrev_b32_e32 v89, 16, v94
	v_add_f32_e32 v86, 1.0, v86
	v_rcp_f32_e32 v86, v86
	v_add_f32_e32 v87, 1.0, v87
	v_rcp_f32_e32 v87, v87
	v_pk_fma_f32 v[70:71], v[76:77], v[88:89], v[70:71] op_sel_hi:[0,1,1]
	v_pk_fma_f32 v[64:65], v[76:77], v[90:91], v[64:65] op_sel_hi:[0,1,1]
	v_lshlrev_b32_e32 v91, 16, v99
	v_pk_mul_f32 v[80:81], v[86:87], v[80:81]
	v_lshlrev_b32_e32 v90, 16, v98
	v_pk_mul_f32 v[70:71], v[70:71], v[80:81]
	v_lshlrev_b32_e32 v80, 16, v78
	v_and_b32_e32 v81, 0xffff0000, v78
	v_mul_f32_e32 v78, 0xbfb8aa3b, v80
	v_exp_f32_e32 v78, v78
	v_mul_f32_e32 v86, 0xbfb8aa3b, v81
	v_exp_f32_e32 v89, v86
	v_pk_fma_f32 v[66:67], v[76:77], v[90:91], v[66:67] op_sel_hi:[0,1,1]
	v_add_f32_e32 v78, 1.0, v78
	v_rcp_f32_e32 v88, v78
	v_add_f32_e32 v78, 1.0, v89
	v_rcp_f32_e32 v89, v78
	v_lshlrev_b32_e32 v78, 16, v79
	v_and_b32_e32 v79, 0xffff0000, v79
	v_pk_mul_f32 v[82:83], v[68:69], v[68:69]
	v_pk_mul_f32 v[80:81], v[88:89], v[80:81]
	v_pk_mul_f32 v[86:87], v[70:71], v[70:71]
	v_pk_mul_f32 v[64:65], v[64:65], v[80:81]
	v_mul_f32_e32 v80, 0xbfb8aa3b, v78
	v_exp_f32_e32 v88, v80
	v_mul_f32_e32 v80, 0xbfb8aa3b, v79
	v_exp_f32_e32 v89, v80
	v_pk_mul_f32 v[80:81], v[64:65], v[64:65]
	v_add_f32_e32 v88, 1.0, v88
	v_rcp_f32_e32 v88, v88
	v_add_f32_e32 v89, 1.0, v89
	v_rcp_f32_e32 v89, v89
	s_nop 0
	v_pk_mul_f32 v[78:79], v[88:89], v[78:79]
	v_or_b32_e32 v88, 32, v96
	v_mul_lo_u32 v91, v88, s90
	v_lshlrev_b32_e32 v88, 16, v72
	v_and_b32_e32 v89, 0xffff0000, v72
	v_mul_f32_e32 v72, 0xbfb8aa3b, v88
	v_exp_f32_e32 v72, v72
	v_mul_f32_e32 v90, 0xbfb8aa3b, v89
	v_exp_f32_e32 v90, v90
	v_add_u32_e32 v97, v77, v91
	v_add_f32_e32 v72, 1.0, v72
	v_rcp_f32_e32 v94, v72
	v_add_f32_e32 v72, 1.0, v90
	v_rcp_f32_e32 v95, v72
	v_or_b32_e32 v72, 48, v96
	v_mul_lo_u32 v90, v72, s90
	v_add_u32_e32 v72, v77, v90
	ds_read_u16 v77, v97
	ds_read_u16 v96, v97 offset:144
	ds_read_u16 v98, v97 offset:288
	ds_read_u16 v99, v97 offset:432
	ds_read_u16 v100, v72
	ds_read_u16 v101, v72 offset:144
	ds_read_u16 v102, v72 offset:288
	ds_read_u16 v103, v72 offset:432
	s_waitcnt lgkmcnt(6)
	v_lshlrev_b32_e32 v97, 16, v96
	v_lshlrev_b32_e32 v96, 16, v77
	v_lshlrev_b32_e32 v72, 16, v73
	v_pk_fma_f32 v[56:57], v[76:77], v[96:97], v[56:57] op_sel_hi:[0,1,1]
	v_pk_mul_f32 v[88:89], v[94:95], v[88:89]
	v_and_b32_e32 v73, 0xffff0000, v73
	v_mul_f32_e32 v77, 0xbfb8aa3b, v72
	v_pk_mul_f32 v[56:57], v[56:57], v[88:89]
	v_exp_f32_e32 v77, v77
	v_mul_f32_e32 v88, 0xbfb8aa3b, v73
	v_exp_f32_e32 v95, v88
	s_waitcnt lgkmcnt(4)
	v_lshlrev_b32_e32 v97, 16, v99
	v_add_f32_e32 v77, 1.0, v77
	v_rcp_f32_e32 v94, v77
	v_add_f32_e32 v77, 1.0, v95
	v_rcp_f32_e32 v95, v77
	v_lshlrev_b32_e32 v96, 16, v98
	v_pk_fma_f32 v[58:59], v[76:77], v[96:97], v[58:59] op_sel_hi:[0,1,1]
	s_waitcnt lgkmcnt(2)
	v_lshlrev_b32_e32 v99, 16, v101
	v_pk_mul_f32 v[72:73], v[94:95], v[72:73]
	v_lshlrev_b32_e32 v98, 16, v100
	v_pk_mul_f32 v[58:59], v[58:59], v[72:73]
	v_lshlrev_b32_e32 v72, 16, v74
	v_and_b32_e32 v73, 0xffff0000, v74
	v_mul_f32_e32 v74, 0xbfb8aa3b, v72
	v_exp_f32_e32 v74, v74
	v_mul_f32_e32 v77, 0xbfb8aa3b, v73
	v_exp_f32_e32 v77, v77
	v_pk_mul_f32 v[66:67], v[66:67], v[78:79]
	v_add_f32_e32 v74, 1.0, v74
	v_rcp_f32_e32 v96, v74
	v_add_f32_e32 v74, 1.0, v77
	v_rcp_f32_e32 v97, v74
	v_pk_fma_f32 v[52:53], v[76:77], v[98:99], v[52:53] op_sel_hi:[0,1,1]
	s_waitcnt lgkmcnt(0)
	v_lshlrev_b32_e32 v99, 16, v103
	v_lshlrev_b32_e32 v98, 16, v102
	v_pk_mul_f32 v[72:73], v[96:97], v[72:73]
	v_pk_mul_f32 v[78:79], v[66:67], v[66:67]
	v_pk_mul_f32 v[52:53], v[52:53], v[72:73]
	v_lshlrev_b32_e32 v72, 16, v75
	v_and_b32_e32 v73, 0xffff0000, v75
	v_mul_f32_e32 v74, 0xbfb8aa3b, v72
	v_exp_f32_e32 v77, v74
	v_mul_f32_e32 v74, 0xbfb8aa3b, v73
	v_exp_f32_e32 v97, v74
	v_pk_mul_f32 v[88:89], v[56:57], v[56:57]
	v_add_f32_e32 v77, 1.0, v77
	v_rcp_f32_e32 v96, v77
	v_add_f32_e32 v77, 1.0, v97
	v_rcp_f32_e32 v97, v77
	v_pk_fma_f32 v[54:55], v[76:77], v[98:99], v[54:55] op_sel_hi:[0,1,1]
	v_add_f32_e32 v77, v82, v83
	v_add_f32_e32 v77, v86, v77
	v_add_f32_e32 v77, v87, v77
	v_add_f32_e32 v77, v77, v80
	v_add_f32_e32 v77, v81, v77
	v_add_f32_e32 v77, v78, v77
	v_add_f32_e32 v77, v79, v77
	v_add_f32_e32 v77, v77, v88
	v_pk_mul_f32 v[94:95], v[58:59], v[58:59]
	v_add_f32_e32 v77, v89, v77
	v_add_f32_e32 v77, v94, v77
	v_pk_mul_f32 v[74:75], v[52:53], v[52:53]
	v_pk_mul_f32 v[72:73], v[96:97], v[72:73]
	v_add_f32_e32 v77, v95, v77
	v_pk_mul_f32 v[54:55], v[54:55], v[72:73]
	v_add_f32_e32 v74, v77, v74
	v_pk_mul_f32 v[72:73], v[54:55], v[54:55]
	v_add_f32_e32 v74, v75, v74
	v_add_f32_e32 v72, v72, v74
	v_add_f32_e32 v72, v73, v72
	ds_bpermute_b32 v73, v85, v72
	s_waitcnt lgkmcnt(0)
	v_add_f32_e32 v72, v72, v73
	ds_bpermute_b32 v73, v119, v72
	s_and_saveexec_b64 s[26:27], s[40:41]
	s_cbranch_execz .LBB0_381
	s_waitcnt lgkmcnt(0)
	v_add_f32_e32 v48, v72, v73
	ds_write_b32 v126, v48 offset:4096

.LBB0_445:
	ds_read_b128 v[16:19], v15
	s_waitcnt lgkmcnt(0)
	v_mov_b32_e32 v8, v17
	v_mov_b32_e32 v9, v18
	v_mov_b32_e32 v20, v16
	v_mov_b32_e32 v21, v19
	v_pk_add_f32 v[8:9], v[8:9], v[20:21]
	s_nop 0
	v_add_f32_e32 v8, v8, v9
	s_nop 1
	v_add_f32_dpp v8, v8, v8 quad_perm:[1,0,3,2] row_mask:0xf bank_mask:0xf
	s_nop 1
	v_add_f32_dpp v8, v8, v8 quad_perm:[2,3,0,1] row_mask:0xf bank_mask:0xf
	s_nop 1
	v_add_f32_dpp v8, v8, v8 row_half_mirror row_mask:0xf bank_mask:0xf
	s_nop 1
	v_add_f32_dpp v8, v8, v8 row_mirror row_mask:0xf bank_mask:0xf
	v_mov_b32_e32 v9, v8
	s_nop 1
	v_permlane16_swap_b32_e32 v8, v9
	v_add_f32_e32 v8, v8, v9
	v_mov_b32_e32 v9, v8
	s_nop 1
	v_permlane32_swap_b32_e32 v8, v9
	v_add_f32_e32 v20, v8, v9
	v_fmamk_f32 v9, v20, 0xbb800000, v17
	v_fmamk_f32 v8, v20, 0xbb800000, v16
	v_fmamk_f32 v19, v20, 0xbb800000, v19
	v_fmac_f32_e32 v18, 0xbb800000, v20
	v_pk_mul_f32 v[16:17], v[18:19], v[18:19]
	v_pk_mul_f32 v[20:21], v[8:9], v[8:9]
	s_nop 0
	v_pk_mov_b32 v[22:23], v[20:21], v[16:17] op_sel:[1,0]
	v_mov_b32_e32 v21, v17
	v_pk_add_f32 v[16:17], v[22:23], v[20:21]
	s_nop 0
	v_add_f32_e32 v16, v16, v17
	s_nop 1
	v_add_f32_dpp v16, v16, v16 quad_perm:[1,0,3,2] row_mask:0xf bank_mask:0xf
	s_nop 1
	v_add_f32_dpp v16, v16, v16 quad_perm:[2,3,0,1] row_mask:0xf bank_mask:0xf
	s_nop 1
	v_add_f32_dpp v16, v16, v16 row_half_mirror row_mask:0xf bank_mask:0xf
	s_nop 1
	v_add_f32_dpp v16, v16, v16 row_mirror row_mask:0xf bank_mask:0xf
	v_mov_b32_e32 v17, v16
	s_nop 1
	v_permlane16_swap_b32_e32 v16, v17
	v_add_f32_e32 v16, v16, v17
	v_mov_b32_e32 v17, v16
	s_nop 1
	v_permlane32_swap_b32_e32 v16, v17
	v_add_f32_e32 v16, v16, v17
	v_fmamk_f32 v16, v16, 0x3b800000, v209
	v_cmp_gt_f32_e32 vcc, s5, v16
	v_mul_f32_e32 v17, 0x4f800000, v16
	s_nop 0
	v_cndmask_b32_e32 v16, v16, v17, vcc
	v_sqrt_f32_e32 v17, v16
	s_nop 0
	v_add_u32_e32 v20, -1, v17
	v_fma_f32 v21, -v20, v17, v16
	v_cmp_ge_f32_e64 s[40:41], 0, v21
	v_add_u32_e32 v21, 1, v17
	s_nop 0
	v_cndmask_b32_e64 v20, v17, v20, s[40:41]
	v_fma_f32 v17, -v21, v17, v16
	v_cmp_lt_f32_e64 s[40:41], 0, v17
	s_nop 1
	v_cndmask_b32_e64 v17, v20, v21, s[40:41]
	v_mul_f32_e32 v20, 0x37800000, v17
	v_cndmask_b32_e32 v17, v17, v20, vcc
	v_cmp_class_f32_e32 vcc, v16, v210
	s_nop 1
	v_cndmask_b32_e32 v16, v17, v16, vcc
	v_div_scale_f32 v17, s[24:25], v16, v16, 1.0
	v_rcp_f32_e32 v20, v17
	s_add_i32 s24, s16, s17
	s_ashr_i32 s25, s24, 31
	s_lshl_b64 s[26:27], s[24:25], 11
	v_fma_f32 v21, -v17, v20, 1.0
	v_fmac_f32_e32 v20, v21, v20
	v_div_scale_f32 v21, vcc, 1.0, v16, 1.0
	v_mul_f32_e32 v22, v21, v20
	v_fma_f32 v23, -v17, v22, v21
	v_fmac_f32_e32 v22, v23, v20
	v_fma_f32 v17, -v17, v22, v21
	v_div_fmas_f32 v17, v17, v20, v22
	v_div_fixup_f32 v16, v17, v16, 1.0
	v_pk_mul_f32 v[8:9], v[8:9], v[16:17] op_sel_hi:[1,0]
	v_pk_mul_f32 v[16:17], v[18:19], v[16:17] op_sel_hi:[1,0]
	v_pk_fma_f32 v[8:9], v[0:1], v[8:9], v[4:5]
	v_pk_fma_f32 v[16:17], v[2:3], v[16:17], v[6:7]
	v_mul_f32_e32 v18, 0xbfb8aa3b, v8
	v_mul_f32_e32 v19, 0xbfb8aa3b, v9
	v_exp_f32_e32 v18, v18
	v_exp_f32_e32 v19, v19
	s_add_u32 s26, s42, s26
	s_addc_u32 s27, s43, s27
	v_add_f32_e32 v18, 1.0, v18
	v_add_f32_e32 v19, 1.0, v19
	v_rcp_f32_e32 v18, v18
	v_rcp_f32_e32 v19, v19
	s_mov_b32 s25, 0x5600000
	s_add_i32 s24, s24, 1
	v_pk_mul_f32 v[8:9], v[8:9], v[18:19]
	s_nop 0
	v_cvt_pk_bf16_f32 v8, v8, v9
	v_mul_f32_e32 v9, 0xbfb8aa3b, v16
	v_exp_f32_e32 v9, v9
	s_nop 0
	v_add_f32_e32 v9, 1.0, v9
	v_rcp_f32_e32 v18, v9
	v_mul_f32_e32 v9, 0xbfb8aa3b, v17
	v_exp_f32_e32 v9, v9
	s_nop 0
	v_add_f32_e32 v9, 1.0, v9
	v_rcp_f32_e32 v19, v9
	s_nop 0
	v_pk_mul_f32 v[16:17], v[16:17], v[18:19]
	s_nop 0
	v_cvt_pk_bf16_f32 v9, v16, v17
	v_lshl_add_u64 v[16:17], s[26:27], 0, v[162:163]
	v_add_co_u32_e32 v16, vcc, s25, v16
	s_ashr_i32 s25, s24, 31
	s_nop 0
	v_addc_co_u32_e32 v17, vcc, 0, v17, vcc
	global_store_dwordx2 v[16:17], v[8:9], off offset:1536
	ds_read_b128 v[16:19], v15 offset:1024
	s_lshl_b64 s[24:25], s[24:25], 11
	s_add_u32 s24, s42, s24
	s_addc_u32 s25, s43, s25
	s_add_i32 s17, s17, 2
	s_waitcnt lgkmcnt(0)
	v_mov_b32_e32 v8, v17
	v_mov_b32_e32 v9, v18
	v_mov_b32_e32 v20, v16
	v_mov_b32_e32 v21, v19
	v_pk_add_f32 v[8:9], v[8:9], v[20:21]
	v_add_u32_e32 v15, 0x800, v15
	v_add_f32_e32 v8, v8, v9
	s_cmp_eq_u32 s17, 8
	s_nop 1
	v_add_f32_dpp v8, v8, v8 quad_perm:[1,0,3,2] row_mask:0xf bank_mask:0xf
	s_nop 1
	v_add_f32_dpp v8, v8, v8 quad_perm:[2,3,0,1] row_mask:0xf bank_mask:0xf
	s_nop 1
	v_add_f32_dpp v8, v8, v8 row_half_mirror row_mask:0xf bank_mask:0xf
	s_nop 1
	v_add_f32_dpp v8, v8, v8 row_mirror row_mask:0xf bank_mask:0xf
	v_mov_b32_e32 v9, v8
	s_nop 1
	v_permlane16_swap_b32_e32 v8, v9
	v_add_f32_e32 v8, v8, v9
	v_mov_b32_e32 v9, v8
	s_nop 1
	v_permlane32_swap_b32_e32 v8, v9
	v_add_f32_e32 v20, v8, v9
	v_fmamk_f32 v9, v20, 0xbb800000, v17
	v_fmamk_f32 v8, v20, 0xbb800000, v16
	v_fmamk_f32 v19, v20, 0xbb800000, v19
	v_fmac_f32_e32 v18, 0xbb800000, v20
	v_pk_mul_f32 v[16:17], v[18:19], v[18:19]
	v_pk_mul_f32 v[20:21], v[8:9], v[8:9]
	s_nop 0
	v_pk_mov_b32 v[22:23], v[20:21], v[16:17] op_sel:[1,0]
	v_mov_b32_e32 v21, v17
	v_pk_add_f32 v[16:17], v[22:23], v[20:21]
	s_nop 0
	v_add_f32_e32 v16, v16, v17
	s_nop 1
	v_add_f32_dpp v16, v16, v16 quad_perm:[1,0,3,2] row_mask:0xf bank_mask:0xf
	s_nop 1
	v_add_f32_dpp v16, v16, v16 quad_perm:[2,3,0,1] row_mask:0xf bank_mask:0xf
	s_nop 1
	v_add_f32_dpp v16, v16, v16 row_half_mirror row_mask:0xf bank_mask:0xf
	s_nop 1
	v_add_f32_dpp v16, v16, v16 row_mirror row_mask:0xf bank_mask:0xf
	v_mov_b32_e32 v17, v16
	s_nop 1
	v_permlane16_swap_b32_e32 v16, v17
	v_add_f32_e32 v16, v16, v17
	v_mov_b32_e32 v17, v16
	s_nop 1
	v_permlane32_swap_b32_e32 v16, v17
	v_add_f32_e32 v16, v16, v17
	v_fmamk_f32 v16, v16, 0x3b800000, v209
	v_cmp_gt_f32_e32 vcc, s5, v16
	v_mul_f32_e32 v17, 0x4f800000, v16
	s_nop 0
	v_cndmask_b32_e32 v16, v16, v17, vcc
	v_sqrt_f32_e32 v17, v16
	s_nop 0
	v_add_u32_e32 v20, -1, v17
	v_fma_f32 v21, -v20, v17, v16
	v_cmp_ge_f32_e64 s[40:41], 0, v21
	v_add_u32_e32 v21, 1, v17
	s_nop 0
	v_cndmask_b32_e64 v20, v17, v20, s[40:41]
	v_fma_f32 v17, -v21, v17, v16
	v_cmp_lt_f32_e64 s[40:41], 0, v17
	s_nop 1
	v_cndmask_b32_e64 v17, v20, v21, s[40:41]
	v_mul_f32_e32 v20, 0x37800000, v17
	v_cndmask_b32_e32 v17, v17, v20, vcc
	v_cmp_class_f32_e32 vcc, v16, v210
	s_nop 1
	v_cndmask_b32_e32 v16, v17, v16, vcc
	v_div_scale_f32 v17, s[26:27], v16, v16, 1.0
	v_rcp_f32_e32 v20, v17
	s_nop 0
	v_fma_f32 v21, -v17, v20, 1.0
	v_fmac_f32_e32 v20, v21, v20
	v_div_scale_f32 v21, vcc, 1.0, v16, 1.0
	v_mul_f32_e32 v22, v21, v20
	v_fma_f32 v23, -v17, v22, v21
	v_fmac_f32_e32 v22, v23, v20
	v_fma_f32 v17, -v17, v22, v21
	v_div_fmas_f32 v17, v17, v20, v22
	v_div_fixup_f32 v16, v17, v16, 1.0
	v_pk_mul_f32 v[8:9], v[8:9], v[16:17] op_sel_hi:[1,0]
	v_pk_mul_f32 v[16:17], v[18:19], v[16:17] op_sel_hi:[1,0]
	v_pk_fma_f32 v[8:9], v[0:1], v[8:9], v[4:5]
	v_pk_fma_f32 v[16:17], v[2:3], v[16:17], v[6:7]
	v_mul_f32_e32 v18, 0xbfb8aa3b, v8
	v_mul_f32_e32 v19, 0xbfb8aa3b, v9
	v_exp_f32_e32 v18, v18
	v_exp_f32_e32 v19, v19
	v_add_f32_e32 v18, 1.0, v18
	v_add_f32_e32 v19, 1.0, v19
	v_rcp_f32_e32 v18, v18
	v_rcp_f32_e32 v19, v19
	s_nop 0
	v_pk_mul_f32 v[8:9], v[8:9], v[18:19]
	s_nop 0
	v_cvt_pk_bf16_f32 v8, v8, v9
	v_mul_f32_e32 v9, 0xbfb8aa3b, v16
	v_exp_f32_e32 v9, v9
	s_nop 0
	v_add_f32_e32 v9, 1.0, v9
	v_rcp_f32_e32 v18, v9
	v_mul_f32_e32 v9, 0xbfb8aa3b, v17
	v_exp_f32_e32 v9, v9
	s_nop 0
	v_add_f32_e32 v9, 1.0, v9
	v_rcp_f32_e32 v19, v9
	s_nop 0
	v_pk_mul_f32 v[16:17], v[16:17], v[18:19]
	s_nop 0
	v_cvt_pk_bf16_f32 v9, v16, v17
	v_lshl_add_u64 v[16:17], s[24:25], 0, v[162:163]
	v_add_co_u32_e32 v16, vcc, 0x5600000, v16
	s_nop 1
	v_addc_co_u32_e32 v17, vcc, 0, v17, vcc
	global_store_dwordx2 v[16:17], v[8:9], off offset:1536
	s_cbranch_scc0 .LBB0_445
	s_add_i32 s38, s38, s80
	s_add_i32 s71, s71, s72
	s_add_i32 s73, s73, s81
	s_cmpk_gt_i32 s38, 0xff
	s_barrier
	s_barrier
	s_cbranch_scc0 .LBB0_392
